# speedup vs baseline: 1.0031x; 1.0031x over previous
; __device__ __forceinline__ float bflo(unsigned v) { return __uint_as_float(v << 16); }
; __device__ __forceinline__ float bfhi(unsigned v) { return __uint_as_float(v & 0xffff0000u); }
; __device__ __forceinline__ void phase4(const Params& p, char* shm) {
;     ...
;       for (int b8 = 0; b8 < 2; ++b8) {
;         u32x2 ga[8], gb[8];
; #pragma unroll
;         for (int i = 0; i < 8; ++i) { const int id = tid + (b8 * 8 + i) * NTHR, row = id >> 6, c = id & 63;
;           ga[i] = *reinterpret_cast<const u32x2*>(gsrc + (size_t)row * 4096 + c * 4);
;           gb[i] = *reinterpret_cast<const u32x2*>(gsrc + (size_t)row * 4096 + 2048 + c * 4); }
; #pragma unroll
;         for (int i = 0; i < 8; ++i) { const int id = tid + (b8 * 8 + i) * NTHR, row = id >> 6, c = id & 63;
;           f32x4 rt = { bflo(ga[i][0]) * __builtin_amdgcn_rcpf(bflo(gb[i][0])), bfhi(ga[i][0]) * __builtin_amdgcn_rcpf(bfhi(gb[i][0])),
;                        bflo(ga[i][1]) * __builtin_amdgcn_rcpf(bflo(gb[i][1])), bfhi(ga[i][1]) * __builtin_amdgcn_rcpf(bfhi(gb[i][1])) };
;           *reinterpret_cast<f32x4*>(shm + (row * CF_LD + c * 4) * 4) = rt; }
.LBB0_457:
	s_or_b64 exec, exec, s[30:31]
	s_andn2_b64 vcc, exec, s[20:21]
	s_barrier
	s_cbranch_vccnz .LBB0_450
	v_mov_b32_e32 v187, v1
	s_nop 0
	v_and_b32_e32 v2, 15, v187
	v_lshrrev_b32_e32 v4, 2, v187
	v_and_or_b32 v2, v4, s51, v2
	v_mul_lo_u32 v5, v2, s52
	v_lshrrev_b32_e32 v2, 1, v187
	v_ashrrev_i32_e32 v140, 6, v187
	v_and_b32_e32 v134, 0x60, v2
	v_lshlrev_b32_e32 v2, 2, v187
	v_ashrrev_i32_e32 v141, 31, v140
	v_and_b32_e32 v4, 0xfc, v2
	v_lshlrev_b64 v[136:137], 9, v[140:141]
	v_lshl_add_u64 v[136:137], s[12:13], 0, v[136:137]
	v_lshlrev_b32_e32 v2, 1, v4
	v_lshl_add_u64 v[136:137], v[136:137], 0, v[2:3]
	v_add_co_u32_e32 v138, vcc, s49, v136
	v_add_u32_e32 v141, 0x600, v187
	s_nop 0
	v_addc_co_u32_e32 v139, vcc, 0, v137, vcc
	global_load_dwordx2 v[142:143], v[136:137], off nt
	s_nop 0
	global_load_dwordx2 v[136:137], v[138:139], off nt
	v_add_u32_e32 v138, 0x200, v187
	v_ashrrev_i32_e32 v144, 6, v138
	v_ashrrev_i32_e32 v145, 31, v144
	v_lshlrev_b64 v[138:139], 9, v[144:145]
	v_lshl_add_u64 v[138:139], s[12:13], 0, v[138:139]
	v_lshl_add_u64 v[138:139], v[138:139], 0, v[2:3]
	v_add_co_u32_e32 v146, vcc, s49, v138
	v_ashrrev_i32_e32 v154, 6, v141
	s_nop 0
	v_addc_co_u32_e32 v147, vcc, 0, v139, vcc
	global_load_dwordx2 v[148:149], v[138:139], off nt
	s_nop 0
	global_load_dwordx2 v[146:147], v[146:147], off nt
	v_add_u32_e32 v138, 0x400, v187
	v_ashrrev_i32_e32 v150, 6, v138
	v_ashrrev_i32_e32 v151, 31, v150
	v_lshlrev_b64 v[138:139], 9, v[150:151]
	v_lshl_add_u64 v[138:139], s[12:13], 0, v[138:139]
	v_ashrrev_i32_e32 v155, 31, v154
	v_lshl_add_u64 v[138:139], v[138:139], 0, v[2:3]
	v_lshlrev_b64 v[156:157], 9, v[154:155]
	v_add_co_u32_e32 v152, vcc, s49, v138
	v_lshl_add_u64 v[156:157], s[12:13], 0, v[156:157]
	s_nop 0
	v_addc_co_u32_e32 v153, vcc, 0, v139, vcc
	v_lshl_add_u64 v[156:157], v[156:157], 0, v[2:3]
	v_add_co_u32_e32 v158, vcc, s49, v156
	v_add_u32_e32 v141, 0xa00, v187
	s_nop 0
	v_addc_co_u32_e32 v159, vcc, 0, v157, vcc
	global_load_dwordx2 v[160:161], v[138:139], off nt
	s_nop 0
	global_load_dwordx2 v[152:153], v[152:153], off nt
	s_nop 0
	global_load_dwordx2 v[156:157], v[156:157], off nt
	s_nop 0
	global_load_dwordx2 v[158:159], v[158:159], off nt
	v_add_u32_e32 v138, 0x800, v187
	v_ashrrev_i32_e32 v162, 6, v138
	v_ashrrev_i32_e32 v163, 31, v162
	v_lshlrev_b64 v[138:139], 9, v[162:163]
	v_ashrrev_i32_e32 v166, 6, v141
	v_lshl_add_u64 v[138:139], s[12:13], 0, v[138:139]
	v_ashrrev_i32_e32 v167, 31, v166
	v_lshl_add_u64 v[138:139], v[138:139], 0, v[2:3]
	v_lshlrev_b64 v[168:169], 9, v[166:167]
	v_add_co_u32_e32 v164, vcc, s49, v138
	v_lshl_add_u64 v[168:169], s[12:13], 0, v[168:169]
	s_nop 0
	v_addc_co_u32_e32 v165, vcc, 0, v139, vcc
	v_lshl_add_u64 v[168:169], v[168:169], 0, v[2:3]
	v_add_co_u32_e32 v170, vcc, s49, v168
	v_add_u32_e32 v141, 0xe00, v187
	s_nop 0
	v_addc_co_u32_e32 v171, vcc, 0, v169, vcc
	global_load_dwordx2 v[172:173], v[138:139], off nt
	s_nop 0
	global_load_dwordx2 v[164:165], v[164:165], off nt
	s_nop 0
	global_load_dwordx2 v[168:169], v[168:169], off nt
	s_nop 0
	global_load_dwordx2 v[170:171], v[170:171], off nt
	v_add_u32_e32 v138, 0xc00, v187
	v_ashrrev_i32_e32 v174, 6, v138
	v_ashrrev_i32_e32 v175, 31, v174
	v_lshlrev_b64 v[138:139], 9, v[174:175]
	v_ashrrev_i32_e32 v178, 6, v141
	v_lshl_add_u64 v[138:139], s[12:13], 0, v[138:139]
	v_ashrrev_i32_e32 v179, 31, v178
	v_lshl_add_u64 v[138:139], v[138:139], 0, v[2:3]
	v_lshlrev_b64 v[180:181], 9, v[178:179]
	v_add_co_u32_e32 v176, vcc, s49, v138
	v_lshl_add_u64 v[180:181], s[12:13], 0, v[180:181]
	s_nop 0
	v_addc_co_u32_e32 v177, vcc, 0, v139, vcc
	v_lshl_add_u64 v[180:181], v[180:181], 0, v[2:3]
	v_add_co_u32_e32 v182, vcc, s49, v180
	v_mad_u64_u32 v[140:141], s[20:21], v140, s52, v[4:5]
	s_nop 0
	v_addc_co_u32_e32 v183, vcc, 0, v181, vcc
	global_load_dwordx2 v[184:185], v[138:139], off nt
	s_nop 0
	global_load_dwordx2 v[176:177], v[176:177], off nt
	s_nop 0
	global_load_dwordx2 v[180:181], v[180:181], off nt
	s_nop 0
	global_load_dwordx2 v[182:183], v[182:183], off nt
	v_lshl_add_u32 v140, v140, 2, 0
	v_and_b32_e32 v135, 48, v187
	s_waitcnt vmcnt(15)
	v_lshlrev_b32_e32 v188, 16, v142
	s_waitcnt vmcnt(14)
	v_lshlrev_b32_e32 v138, 16, v136
	v_and_b32_e32 v136, 0xffff0000, v136
	v_rcp_f32_e32 v139, v136
	v_lshlrev_b32_e32 v136, 16, v137
	v_rcp_f32_e32 v138, v138
	v_rcp_f32_e32 v190, v136
	v_and_b32_e32 v136, 0xffff0000, v137
	v_rcp_f32_e32 v191, v136
	v_and_b32_e32 v189, 0xffff0000, v142
	v_pk_mul_f32 v[136:137], v[138:139], v[188:189]
	v_lshlrev_b32_e32 v138, 16, v143
	v_and_b32_e32 v139, 0xffff0000, v143
	v_pk_mul_f32 v[138:139], v[190:191], v[138:139]
	ds_write_b128 v140, v[136:139]
	s_waitcnt vmcnt(12)
	v_lshlrev_b32_e32 v136, 16, v146
	v_and_b32_e32 v137, 0xffff0000, v146
	v_rcp_f32_e32 v136, v136
	v_rcp_f32_e32 v137, v137
	v_lshlrev_b32_e32 v140, 16, v147
	v_and_b32_e32 v141, 0xffff0000, v147
	v_rcp_f32_e32 v140, v140
	v_rcp_f32_e32 v141, v141
	v_lshlrev_b32_e32 v138, 16, v148
	v_and_b32_e32 v139, 0xffff0000, v148
	v_pk_mul_f32 v[136:137], v[136:137], v[138:139]
	v_lshlrev_b32_e32 v138, 16, v149
	v_and_b32_e32 v139, 0xffff0000, v149
	v_pk_mul_f32 v[138:139], v[140:141], v[138:139]
	v_mad_u64_u32 v[140:141], s[20:21], v144, s52, v[4:5]
	v_lshl_add_u32 v140, v140, 2, 0
	ds_write_b128 v140, v[136:139]
	s_waitcnt vmcnt(10)
	v_lshlrev_b32_e32 v136, 16, v152
	v_and_b32_e32 v137, 0xffff0000, v152
	v_rcp_f32_e32 v136, v136
	v_rcp_f32_e32 v137, v137
	v_lshlrev_b32_e32 v140, 16, v153
	v_and_b32_e32 v141, 0xffff0000, v153
	v_rcp_f32_e32 v140, v140
	v_rcp_f32_e32 v141, v141
	v_lshlrev_b32_e32 v138, 16, v160
	v_and_b32_e32 v139, 0xffff0000, v160
	v_pk_mul_f32 v[136:137], v[136:137], v[138:139]
	v_lshlrev_b32_e32 v138, 16, v161
	v_and_b32_e32 v139, 0xffff0000, v161
	v_pk_mul_f32 v[138:139], v[140:141], v[138:139]
	v_mad_u64_u32 v[140:141], s[20:21], v150, s52, v[4:5]
	v_lshl_add_u32 v140, v140, 2, 0
	ds_write_b128 v140, v[136:139]
	s_waitcnt vmcnt(8)
; __device__ __forceinline__ float bflo(unsigned v) { return __uint_as_float(v << 16); }
; __device__ __forceinline__ float bfhi(unsigned v) { return __uint_as_float(v & 0xffff0000u); }
; __device__ __forceinline__ void phase4(const Params& p, char* shm) {
;     ...
;         for (int i = 0; i < 8; ++i) { const int id = tid + (b8 * 8 + i) * NTHR, row = id >> 6, c = id & 63;
;           ga[i] = *reinterpret_cast<const u32x2*>(gsrc + (size_t)row * 4096 + c * 4);
;           gb[i] = *reinterpret_cast<const u32x2*>(gsrc + (size_t)row * 4096 + 2048 + c * 4); }
;     ...
;         for (int i = 0; i < 8; ++i) { const int id = tid + (b8 * 8 + i) * NTHR, row = id >> 6, c = id & 63;
;           f32x4 rt = { bflo(ga[i][0]) * __builtin_amdgcn_rcpf(bflo(gb[i][0])), bfhi(ga[i][0]) * __builtin_amdgcn_rcpf(bfhi(gb[i][0])),
;                        bflo(ga[i][1]) * __builtin_amdgcn_rcpf(bflo(gb[i][1])), bfhi(ga[i][1]) * __builtin_amdgcn_rcpf(bfhi(gb[i][1])) };
;           *reinterpret_cast<f32x4*>(shm + (row * CF_LD + c * 4) * 4) = rt; }
	v_lshlrev_b32_e32 v136, 16, v158
	v_and_b32_e32 v137, 0xffff0000, v158
	v_rcp_f32_e32 v136, v136
	v_rcp_f32_e32 v137, v137
	v_lshlrev_b32_e32 v140, 16, v159
	v_and_b32_e32 v141, 0xffff0000, v159
	v_rcp_f32_e32 v140, v140
	v_rcp_f32_e32 v141, v141
	v_lshlrev_b32_e32 v138, 16, v156
	v_and_b32_e32 v139, 0xffff0000, v156
	v_pk_mul_f32 v[136:137], v[136:137], v[138:139]
	v_lshlrev_b32_e32 v138, 16, v157
	v_and_b32_e32 v139, 0xffff0000, v157
	v_pk_mul_f32 v[138:139], v[140:141], v[138:139]
	v_mad_u64_u32 v[140:141], s[20:21], v154, s52, v[4:5]
	v_lshl_add_u32 v140, v140, 2, 0
	ds_write_b128 v140, v[136:139]
	s_waitcnt vmcnt(6)
	v_lshlrev_b32_e32 v136, 16, v164
	v_and_b32_e32 v137, 0xffff0000, v164
	v_rcp_f32_e32 v136, v136
	v_rcp_f32_e32 v137, v137
	v_lshlrev_b32_e32 v140, 16, v165
	v_and_b32_e32 v141, 0xffff0000, v165
	v_rcp_f32_e32 v140, v140
	v_rcp_f32_e32 v141, v141
	v_lshlrev_b32_e32 v138, 16, v172
	v_and_b32_e32 v139, 0xffff0000, v172
	v_pk_mul_f32 v[136:137], v[136:137], v[138:139]
	v_lshlrev_b32_e32 v138, 16, v173
	v_and_b32_e32 v139, 0xffff0000, v173
	v_pk_mul_f32 v[138:139], v[140:141], v[138:139]
	v_mad_u64_u32 v[140:141], s[20:21], v162, s52, v[4:5]
	v_lshl_add_u32 v140, v140, 2, 0
	ds_write_b128 v140, v[136:139]
	s_waitcnt vmcnt(4)
	v_lshlrev_b32_e32 v136, 16, v170
	v_and_b32_e32 v137, 0xffff0000, v170
	v_rcp_f32_e32 v136, v136
	v_rcp_f32_e32 v137, v137
	v_lshlrev_b32_e32 v140, 16, v171
	v_and_b32_e32 v141, 0xffff0000, v171
	v_rcp_f32_e32 v140, v140
	v_rcp_f32_e32 v141, v141
	v_lshlrev_b32_e32 v138, 16, v168
	v_and_b32_e32 v139, 0xffff0000, v168
	v_pk_mul_f32 v[136:137], v[136:137], v[138:139]
	v_lshlrev_b32_e32 v138, 16, v169
	v_and_b32_e32 v139, 0xffff0000, v169
	v_pk_mul_f32 v[138:139], v[140:141], v[138:139]
	v_mad_u64_u32 v[140:141], s[20:21], v166, s52, v[4:5]
	v_lshl_add_u32 v140, v140, 2, 0
	ds_write_b128 v140, v[136:139]
	s_waitcnt vmcnt(2)
	v_lshlrev_b32_e32 v136, 16, v176
	v_and_b32_e32 v137, 0xffff0000, v176
	v_rcp_f32_e32 v136, v136
	v_rcp_f32_e32 v137, v137
	v_lshlrev_b32_e32 v140, 16, v177
	v_and_b32_e32 v141, 0xffff0000, v177
	v_rcp_f32_e32 v140, v140
	v_rcp_f32_e32 v141, v141
	v_lshlrev_b32_e32 v138, 16, v184
	v_and_b32_e32 v139, 0xffff0000, v184
	v_pk_mul_f32 v[136:137], v[136:137], v[138:139]
	v_lshlrev_b32_e32 v138, 16, v185
	v_and_b32_e32 v139, 0xffff0000, v185
	v_pk_mul_f32 v[138:139], v[140:141], v[138:139]
	v_mad_u64_u32 v[140:141], s[20:21], v174, s52, v[4:5]
	v_lshl_add_u32 v140, v140, 2, 0
	ds_write_b128 v140, v[136:139]
	s_waitcnt vmcnt(0)
	v_lshlrev_b32_e32 v136, 16, v182
	v_and_b32_e32 v137, 0xffff0000, v182
	v_rcp_f32_e32 v136, v136
	v_rcp_f32_e32 v137, v137
	v_lshlrev_b32_e32 v140, 16, v183
	v_and_b32_e32 v141, 0xffff0000, v183
	v_rcp_f32_e32 v140, v140
	v_rcp_f32_e32 v141, v141
	v_lshlrev_b32_e32 v138, 16, v180
	v_and_b32_e32 v139, 0xffff0000, v180
	v_pk_mul_f32 v[136:137], v[136:137], v[138:139]
	v_lshlrev_b32_e32 v138, 16, v181
	v_and_b32_e32 v139, 0xffff0000, v181
	v_pk_mul_f32 v[138:139], v[140:141], v[138:139]
	v_mad_u64_u32 v[140:141], s[20:21], v178, s52, v[4:5]
	v_lshl_add_u32 v140, v140, 2, 0
	ds_write_b128 v140, v[136:139]
	v_add_u32_e32 v136, 0x1000, v187
	v_ashrrev_i32_e32 v140, 6, v136
	v_ashrrev_i32_e32 v141, 31, v140
	v_lshlrev_b64 v[136:137], 9, v[140:141]
	v_lshl_add_u64 v[136:137], s[12:13], 0, v[136:137]
	v_lshl_add_u64 v[136:137], v[136:137], 0, v[2:3]
	v_add_co_u32_e32 v138, vcc, s49, v136
	v_add_u32_e32 v141, 0x1600, v187
	s_nop 0
	v_addc_co_u32_e32 v139, vcc, 0, v137, vcc
	global_load_dwordx2 v[142:143], v[136:137], off nt
	s_nop 0
	global_load_dwordx2 v[136:137], v[138:139], off nt
	v_add_u32_e32 v138, 0x1200, v187
	v_ashrrev_i32_e32 v144, 6, v138
	v_ashrrev_i32_e32 v145, 31, v144
	v_lshlrev_b64 v[138:139], 9, v[144:145]
	v_lshl_add_u64 v[138:139], s[12:13], 0, v[138:139]
	v_lshl_add_u64 v[138:139], v[138:139], 0, v[2:3]
	v_add_co_u32_e32 v146, vcc, s49, v138
	v_ashrrev_i32_e32 v154, 6, v141
	s_nop 0
	v_addc_co_u32_e32 v147, vcc, 0, v139, vcc
	global_load_dwordx2 v[148:149], v[138:139], off nt
	s_nop 0
	global_load_dwordx2 v[146:147], v[146:147], off nt
	v_add_u32_e32 v138, 0x1400, v187
	v_ashrrev_i32_e32 v150, 6, v138
	v_ashrrev_i32_e32 v151, 31, v150
	v_lshlrev_b64 v[138:139], 9, v[150:151]
	v_lshl_add_u64 v[138:139], s[12:13], 0, v[138:139]
	v_ashrrev_i32_e32 v155, 31, v154
	v_lshl_add_u64 v[138:139], v[138:139], 0, v[2:3]
	v_lshlrev_b64 v[156:157], 9, v[154:155]
	v_add_co_u32_e32 v152, vcc, s49, v138
	v_lshl_add_u64 v[156:157], s[12:13], 0, v[156:157]
	s_nop 0
	v_addc_co_u32_e32 v153, vcc, 0, v139, vcc
	v_lshl_add_u64 v[156:157], v[156:157], 0, v[2:3]
	v_add_co_u32_e32 v158, vcc, s49, v156
	v_add_u32_e32 v141, 0x1a00, v187
	s_nop 0
	v_addc_co_u32_e32 v159, vcc, 0, v157, vcc
	global_load_dwordx2 v[160:161], v[138:139], off nt
	s_nop 0
	global_load_dwordx2 v[152:153], v[152:153], off nt
	s_nop 0
	global_load_dwordx2 v[156:157], v[156:157], off nt
	s_nop 0
	global_load_dwordx2 v[158:159], v[158:159], off nt
	v_add_u32_e32 v138, 0x1800, v187
	v_ashrrev_i32_e32 v162, 6, v138
	v_ashrrev_i32_e32 v163, 31, v162
	v_lshlrev_b64 v[138:139], 9, v[162:163]
	v_ashrrev_i32_e32 v166, 6, v141
	v_lshl_add_u64 v[138:139], s[12:13], 0, v[138:139]
	v_ashrrev_i32_e32 v167, 31, v166
	v_lshl_add_u64 v[138:139], v[138:139], 0, v[2:3]
	v_lshlrev_b64 v[168:169], 9, v[166:167]
	v_add_co_u32_e32 v164, vcc, s49, v138
	v_lshl_add_u64 v[168:169], s[12:13], 0, v[168:169]
	s_nop 0
	v_addc_co_u32_e32 v165, vcc, 0, v139, vcc
	v_lshl_add_u64 v[168:169], v[168:169], 0, v[2:3]
	v_add_co_u32_e32 v170, vcc, s49, v168
	v_add_u32_e32 v141, 0x1e00, v187
	s_nop 0
	v_addc_co_u32_e32 v171, vcc, 0, v169, vcc
	global_load_dwordx2 v[172:173], v[138:139], off nt
	s_nop 0
	global_load_dwordx2 v[164:165], v[164:165], off nt
	s_nop 0
	global_load_dwordx2 v[168:169], v[168:169], off nt
	s_nop 0
	global_load_dwordx2 v[170:171], v[170:171], off nt
	v_add_u32_e32 v138, 0x1c00, v187
	v_ashrrev_i32_e32 v174, 6, v138
	v_ashrrev_i32_e32 v175, 31, v174
	v_lshlrev_b64 v[138:139], 9, v[174:175]
	v_ashrrev_i32_e32 v178, 6, v141
	v_lshl_add_u64 v[138:139], s[12:13], 0, v[138:139]
	v_ashrrev_i32_e32 v179, 31, v178
	v_lshl_add_u64 v[138:139], v[138:139], 0, v[2:3]
	v_lshlrev_b64 v[180:181], 9, v[178:179]
	v_add_co_u32_e32 v176, vcc, s49, v138
	v_lshl_add_u64 v[180:181], s[12:13], 0, v[180:181]
	s_nop 0
	v_addc_co_u32_e32 v177, vcc, 0, v139, vcc
	v_lshl_add_u64 v[180:181], v[180:181], 0, v[2:3]
	v_add_co_u32_e32 v182, vcc, s49, v180
	v_mad_u64_u32 v[140:141], s[20:21], v140, s52, v[4:5]
	s_nop 0
	v_addc_co_u32_e32 v183, vcc, 0, v181, vcc
	global_load_dwordx2 v[184:185], v[138:139], off nt
	s_nop 0
	global_load_dwordx2 v[176:177], v[176:177], off nt
	s_nop 0
	global_load_dwordx2 v[180:181], v[180:181], off nt
	s_nop 0
	global_load_dwordx2 v[182:183], v[182:183], off nt
	v_mov_b32_e32 v187, v1
	s_waitcnt vmcnt(15)
; __device__ __forceinline__ float bflo(unsigned v) { return __uint_as_float(v << 16); }
; __device__ __forceinline__ float bfhi(unsigned v) { return __uint_as_float(v & 0xffff0000u); }
; __device__ __forceinline__ void phase4(const Params& p, char* shm) {
;     ...
;         for (int i = 0; i < 8; ++i) { const int id = tid + (b8 * 8 + i) * NTHR, row = id >> 6, c = id & 63;
;           f32x4 rt = { bflo(ga[i][0]) * __builtin_amdgcn_rcpf(bflo(gb[i][0])), bfhi(ga[i][0]) * __builtin_amdgcn_rcpf(bfhi(gb[i][0])),
;                        bflo(ga[i][1]) * __builtin_amdgcn_rcpf(bflo(gb[i][1])), bfhi(ga[i][1]) * __builtin_amdgcn_rcpf(bfhi(gb[i][1])) };
;           *reinterpret_cast<f32x4*>(shm + (row * CF_LD + c * 4) * 4) = rt; }
;       }
;       __syncthreads();
	v_lshlrev_b32_e32 v188, 16, v142
	s_waitcnt vmcnt(14)
	v_lshlrev_b32_e32 v2, 16, v136
	v_rcp_f32_e32 v138, v2
	v_and_b32_e32 v2, 0xffff0000, v136
	v_rcp_f32_e32 v139, v2
	v_lshlrev_b32_e32 v2, 16, v137
	v_rcp_f32_e32 v190, v2
	v_and_b32_e32 v2, 0xffff0000, v137
	v_rcp_f32_e32 v191, v2
	v_and_b32_e32 v189, 0xffff0000, v142
	v_pk_mul_f32 v[136:137], v[138:139], v[188:189]
	v_lshlrev_b32_e32 v138, 16, v143
	v_and_b32_e32 v139, 0xffff0000, v143
	v_pk_mul_f32 v[138:139], v[190:191], v[138:139]
	v_lshl_add_u32 v2, v140, 2, 0
	ds_write_b128 v2, v[136:139]
	s_waitcnt vmcnt(12)
	v_lshlrev_b32_e32 v2, 16, v146
	v_rcp_f32_e32 v136, v2
	v_and_b32_e32 v2, 0xffff0000, v146
	v_rcp_f32_e32 v137, v2
	v_lshlrev_b32_e32 v2, 16, v147
	v_rcp_f32_e32 v140, v2
	v_and_b32_e32 v2, 0xffff0000, v147
	v_rcp_f32_e32 v141, v2
	v_lshlrev_b32_e32 v138, 16, v148
	v_and_b32_e32 v139, 0xffff0000, v148
	v_pk_mul_f32 v[136:137], v[136:137], v[138:139]
	v_lshlrev_b32_e32 v138, 16, v149
	v_and_b32_e32 v139, 0xffff0000, v149
	v_pk_mul_f32 v[138:139], v[140:141], v[138:139]
	v_mad_u64_u32 v[140:141], s[20:21], v144, s52, v[4:5]
	v_lshl_add_u32 v2, v140, 2, 0
	ds_write_b128 v2, v[136:139]
	s_waitcnt vmcnt(10)
	v_lshlrev_b32_e32 v2, 16, v152
	v_rcp_f32_e32 v136, v2
	v_and_b32_e32 v2, 0xffff0000, v152
	v_rcp_f32_e32 v137, v2
	v_lshlrev_b32_e32 v2, 16, v153
	v_rcp_f32_e32 v140, v2
	v_and_b32_e32 v2, 0xffff0000, v153
	v_rcp_f32_e32 v141, v2
	v_lshlrev_b32_e32 v138, 16, v160
	v_and_b32_e32 v139, 0xffff0000, v160
	v_pk_mul_f32 v[136:137], v[136:137], v[138:139]
	v_lshlrev_b32_e32 v138, 16, v161
	v_and_b32_e32 v139, 0xffff0000, v161
	v_pk_mul_f32 v[138:139], v[140:141], v[138:139]
	v_mad_u64_u32 v[140:141], s[20:21], v150, s52, v[4:5]
	v_lshl_add_u32 v2, v140, 2, 0
	ds_write_b128 v2, v[136:139]
	s_waitcnt vmcnt(8)
	v_lshlrev_b32_e32 v2, 16, v158
	v_rcp_f32_e32 v136, v2
	v_and_b32_e32 v2, 0xffff0000, v158
	v_rcp_f32_e32 v137, v2
	v_lshlrev_b32_e32 v2, 16, v159
	v_rcp_f32_e32 v140, v2
	v_and_b32_e32 v2, 0xffff0000, v159
	v_rcp_f32_e32 v141, v2
	v_lshlrev_b32_e32 v138, 16, v156
	v_and_b32_e32 v139, 0xffff0000, v156
	v_pk_mul_f32 v[136:137], v[136:137], v[138:139]
	v_lshlrev_b32_e32 v138, 16, v157
	v_and_b32_e32 v139, 0xffff0000, v157
	v_pk_mul_f32 v[138:139], v[140:141], v[138:139]
	v_mad_u64_u32 v[140:141], s[20:21], v154, s52, v[4:5]
	v_lshl_add_u32 v2, v140, 2, 0
	ds_write_b128 v2, v[136:139]
	s_waitcnt vmcnt(6)
	v_lshlrev_b32_e32 v2, 16, v164
	v_rcp_f32_e32 v136, v2
	v_and_b32_e32 v2, 0xffff0000, v164
	v_rcp_f32_e32 v137, v2
	v_lshlrev_b32_e32 v2, 16, v165
	v_rcp_f32_e32 v140, v2
	v_and_b32_e32 v2, 0xffff0000, v165
	v_rcp_f32_e32 v141, v2
	v_lshlrev_b32_e32 v138, 16, v172
	v_and_b32_e32 v139, 0xffff0000, v172
	v_pk_mul_f32 v[136:137], v[136:137], v[138:139]
	v_lshlrev_b32_e32 v138, 16, v173
	v_and_b32_e32 v139, 0xffff0000, v173
	v_pk_mul_f32 v[138:139], v[140:141], v[138:139]
	v_mad_u64_u32 v[140:141], s[20:21], v162, s52, v[4:5]
	v_lshl_add_u32 v2, v140, 2, 0
	ds_write_b128 v2, v[136:139]
	s_waitcnt vmcnt(4)
	v_lshlrev_b32_e32 v2, 16, v170
	v_rcp_f32_e32 v136, v2
	v_and_b32_e32 v2, 0xffff0000, v170
	v_rcp_f32_e32 v137, v2
	v_lshlrev_b32_e32 v2, 16, v171
	v_rcp_f32_e32 v140, v2
	v_and_b32_e32 v2, 0xffff0000, v171
	v_rcp_f32_e32 v141, v2
	v_lshlrev_b32_e32 v138, 16, v168
	v_and_b32_e32 v139, 0xffff0000, v168
	v_pk_mul_f32 v[136:137], v[136:137], v[138:139]
	v_lshlrev_b32_e32 v138, 16, v169
	v_and_b32_e32 v139, 0xffff0000, v169
	v_pk_mul_f32 v[138:139], v[140:141], v[138:139]
	v_mad_u64_u32 v[140:141], s[20:21], v166, s52, v[4:5]
	v_lshl_add_u32 v2, v140, 2, 0
	ds_write_b128 v2, v[136:139]
	s_waitcnt vmcnt(2)
	v_lshlrev_b32_e32 v2, 16, v176
	v_rcp_f32_e32 v136, v2
	v_and_b32_e32 v2, 0xffff0000, v176
	v_rcp_f32_e32 v137, v2
	v_lshlrev_b32_e32 v2, 16, v177
	v_rcp_f32_e32 v140, v2
	v_and_b32_e32 v2, 0xffff0000, v177
	v_rcp_f32_e32 v141, v2
	v_lshlrev_b32_e32 v138, 16, v184
	v_and_b32_e32 v139, 0xffff0000, v184
	v_pk_mul_f32 v[136:137], v[136:137], v[138:139]
	v_lshlrev_b32_e32 v138, 16, v185
	v_and_b32_e32 v139, 0xffff0000, v185
	v_pk_mul_f32 v[138:139], v[140:141], v[138:139]
	v_mad_u64_u32 v[140:141], s[20:21], v174, s52, v[4:5]
	v_lshl_add_u32 v2, v140, 2, 0
	ds_write_b128 v2, v[136:139]
	s_waitcnt vmcnt(0)
	v_lshlrev_b32_e32 v2, 16, v182
	v_rcp_f32_e32 v136, v2
	v_and_b32_e32 v2, 0xffff0000, v182
	v_rcp_f32_e32 v137, v2
	v_lshlrev_b32_e32 v2, 16, v183
	v_rcp_f32_e32 v140, v2
	v_and_b32_e32 v2, 0xffff0000, v183
	v_rcp_f32_e32 v141, v2
	v_lshlrev_b32_e32 v138, 16, v180
	v_and_b32_e32 v139, 0xffff0000, v180
	v_pk_mul_f32 v[136:137], v[136:137], v[138:139]
	v_lshlrev_b32_e32 v138, 16, v181
	v_and_b32_e32 v139, 0xffff0000, v181
	v_pk_mul_f32 v[138:139], v[140:141], v[138:139]
	v_mad_u64_u32 v[140:141], s[20:21], v178, s52, v[4:5]
	v_lshl_add_u32 v2, v140, 2, 0
	ds_write_b128 v2, v[136:139]
	v_add_lshl_u32 v2, v5, v134, 2
	v_add3_u32 v2, 0, v135, v2
	s_waitcnt lgkmcnt(0)
	s_barrier
; __device__ __forceinline__ void phase4(const Params& p, char* shm) {
;     ...
;         for (int i = 0; i < 8; ++i) { const int id = tid + (b8 * 8 + i) * NTHR, row = id >> 6, c = id & 63;
;           ga[i] = *reinterpret_cast<const u32x2*>(gsrc + (size_t)row * 4096 + c * 4);
;           gb[i] = *reinterpret_cast<const u32x2*>(gsrc + (size_t)row * 4096 + 2048 + c * 4); }
;     ...
; #pragma unroll
;       for (int bj = 0; bj < 2; ++bj)
; #pragma unroll
;         for (int m = 0; m < 4; ++m)
; #pragma unroll
;           for (int n = 0; n < 2; ++n) acc[ai][bj][m][n] *= *(const f32x4*)(cfb + CF_OFF(bj, m, n));
;       __syncthreads();
	ds_read_b128 v[134:137], v2
	ds_read_b128 v[138:141], v2 offset:64
	ds_read_b128 v[142:145], v2 offset:16640
	ds_read_b128 v[146:149], v2 offset:33792
	s_waitcnt lgkmcnt(3)
	v_pk_mul_f32 v[132:133], v[132:133], v[136:137]
	v_pk_mul_f32 v[130:131], v[130:131], v[134:135]
	s_waitcnt lgkmcnt(2)
	v_pk_mul_f32 v[128:129], v[128:129], v[140:141]
	ds_read_b128 v[134:137], v2 offset:16704
	v_pk_mul_f32 v[126:127], v[126:127], v[138:139]
	ds_read_b128 v[138:141], v2 offset:33280
	s_waitcnt lgkmcnt(3)
	v_pk_mul_f32 v[124:125], v[124:125], v[144:145]
	v_pk_mul_f32 v[122:123], v[122:123], v[142:143]
	s_waitcnt lgkmcnt(1)
	v_pk_mul_f32 v[120:121], v[120:121], v[136:137]
	ds_read_b128 v[142:145], v2 offset:33344
	v_pk_mul_f32 v[118:119], v[118:119], v[134:135]
	s_waitcnt lgkmcnt(1)
	v_pk_mul_f32 v[116:117], v[116:117], v[140:141]
	ds_read_b128 v[134:137], v2 offset:49920
	v_pk_mul_f32 v[114:115], v[114:115], v[138:139]
	ds_read_b128 v[138:141], v2 offset:49984
	s_waitcnt lgkmcnt(2)
	v_pk_mul_f32 v[112:113], v[112:113], v[144:145]
	v_pk_mul_f32 v[110:111], v[110:111], v[142:143]
	ds_read_b128 v[142:145], v2 offset:512
	s_waitcnt lgkmcnt(2)
	v_pk_mul_f32 v[108:109], v[108:109], v[136:137]
	s_waitcnt lgkmcnt(1)
	v_pk_mul_f32 v[104:105], v[104:105], v[140:141]
	v_pk_mul_f32 v[102:103], v[102:103], v[138:139]
	ds_read_b128 v[138:141], v2 offset:17152
	v_pk_mul_f32 v[106:107], v[106:107], v[134:135]
	ds_read_b128 v[134:137], v2 offset:576
	s_waitcnt lgkmcnt(2)
	v_pk_mul_f32 v[100:101], v[100:101], v[144:145]
	v_pk_mul_f32 v[98:99], v[98:99], v[142:143]
	ds_read_b128 v[142:145], v2 offset:17216
	s_waitcnt lgkmcnt(2)
	v_pk_mul_f32 v[92:93], v[92:93], v[140:141]
	v_pk_mul_f32 v[90:91], v[90:91], v[138:139]
	ds_read_b128 v[138:141], v2 offset:33856
	s_waitcnt lgkmcnt(2)
	v_pk_mul_f32 v[96:97], v[96:97], v[136:137]
	v_pk_mul_f32 v[94:95], v[94:95], v[134:135]
	ds_read_b128 v[134:137], v2 offset:50432
	v_pk_mul_f32 v[82:83], v[82:83], v[146:147]
	s_waitcnt lgkmcnt(1)
	v_pk_mul_f32 v[80:81], v[80:81], v[140:141]
	v_pk_mul_f32 v[78:79], v[78:79], v[138:139]
	ds_read_b128 v[138:141], v2 offset:50496
	s_waitcnt lgkmcnt(0)
	s_barrier
	v_pk_mul_f32 v[76:77], v[76:77], v[136:137]
	v_and_b32_e32 v2, 15, v187
	v_lshrrev_b32_e32 v4, 2, v187
	v_and_or_b32 v2, v4, s51, v2
	v_mul_lo_u32 v5, v2, s52
	v_lshrrev_b32_e32 v2, 1, v187
	v_ashrrev_i32_e32 v146, 6, v187
	v_and_b32_e32 v136, 0x60, v2
	v_lshlrev_b32_e32 v2, 2, v187
	v_ashrrev_i32_e32 v147, 31, v146
	v_pk_mul_f32 v[86:87], v[86:87], v[142:143]
	v_and_b32_e32 v4, 0xfc, v2
	v_lshlrev_b64 v[142:143], 9, v[146:147]
	v_lshl_add_u64 v[142:143], s[14:15], 0, v[142:143]
	v_lshlrev_b32_e32 v2, 1, v4
	v_lshl_add_u64 v[142:143], v[142:143], 0, v[2:3]
	v_pk_mul_f32 v[88:89], v[88:89], v[144:145]
	v_add_co_u32_e32 v144, vcc, s49, v142
	v_pk_mul_f32 v[84:85], v[84:85], v[148:149]
	s_nop 0
	v_addc_co_u32_e32 v145, vcc, 0, v143, vcc
	global_load_dwordx2 v[148:149], v[142:143], off nt
	s_nop 0
	global_load_dwordx2 v[142:143], v[144:145], off nt
	v_add_u32_e32 v144, 0x200, v187
	v_ashrrev_i32_e32 v150, 6, v144
	v_ashrrev_i32_e32 v151, 31, v150
	v_lshlrev_b64 v[144:145], 9, v[150:151]
	v_lshl_add_u64 v[144:145], s[14:15], 0, v[144:145]
	v_lshl_add_u64 v[144:145], v[144:145], 0, v[2:3]
	v_add_co_u32_e32 v152, vcc, s49, v144
	v_add_u32_e32 v147, 0x600, v187
	s_nop 0
	v_addc_co_u32_e32 v153, vcc, 0, v145, vcc
	global_load_dwordx2 v[154:155], v[144:145], off nt
	s_nop 0
	global_load_dwordx2 v[152:153], v[152:153], off nt
	v_add_u32_e32 v144, 0x400, v187
	v_ashrrev_i32_e32 v156, 6, v144
	v_ashrrev_i32_e32 v157, 31, v156
	v_lshlrev_b64 v[144:145], 9, v[156:157]
	v_ashrrev_i32_e32 v160, 6, v147
	v_lshl_add_u64 v[144:145], s[14:15], 0, v[144:145]
	v_ashrrev_i32_e32 v161, 31, v160
	v_lshl_add_u64 v[144:145], v[144:145], 0, v[2:3]
	v_lshlrev_b64 v[162:163], 9, v[160:161]
	v_add_co_u32_e32 v158, vcc, s49, v144
	v_lshl_add_u64 v[162:163], s[14:15], 0, v[162:163]
	s_nop 0
	v_addc_co_u32_e32 v159, vcc, 0, v145, vcc
	v_lshl_add_u64 v[162:163], v[162:163], 0, v[2:3]
	v_add_co_u32_e32 v164, vcc, s49, v162
	v_add_u32_e32 v147, 0xa00, v187
	s_nop 0
	v_addc_co_u32_e32 v165, vcc, 0, v163, vcc
	global_load_dwordx2 v[166:167], v[144:145], off nt
	s_nop 0
	global_load_dwordx2 v[158:159], v[158:159], off nt
	s_nop 0
	global_load_dwordx2 v[162:163], v[162:163], off nt
	s_nop 0
	global_load_dwordx2 v[164:165], v[164:165], off nt
	v_add_u32_e32 v144, 0x800, v187
	v_ashrrev_i32_e32 v168, 6, v144
	v_ashrrev_i32_e32 v169, 31, v168
	v_lshlrev_b64 v[144:145], 9, v[168:169]
	v_ashrrev_i32_e32 v172, 6, v147
	v_lshl_add_u64 v[144:145], s[14:15], 0, v[144:145]
	v_ashrrev_i32_e32 v173, 31, v172
	v_lshl_add_u64 v[144:145], v[144:145], 0, v[2:3]
	v_lshlrev_b64 v[174:175], 9, v[172:173]
	v_add_co_u32_e32 v170, vcc, s49, v144
	v_lshl_add_u64 v[174:175], s[14:15], 0, v[174:175]
	s_nop 0
	v_addc_co_u32_e32 v171, vcc, 0, v145, vcc
	v_lshl_add_u64 v[174:175], v[174:175], 0, v[2:3]
	v_add_co_u32_e32 v176, vcc, s49, v174
	v_add_u32_e32 v147, 0xe00, v187
	s_nop 0
	v_addc_co_u32_e32 v177, vcc, 0, v175, vcc
	global_load_dwordx2 v[178:179], v[144:145], off nt
	s_nop 0
	global_load_dwordx2 v[170:171], v[170:171], off nt
	s_nop 0
	global_load_dwordx2 v[174:175], v[174:175], off nt
	s_nop 0
	global_load_dwordx2 v[176:177], v[176:177], off nt
	v_add_u32_e32 v144, 0xc00, v187
	v_ashrrev_i32_e32 v180, 6, v144
	v_ashrrev_i32_e32 v181, 31, v180
	v_lshlrev_b64 v[144:145], 9, v[180:181]
	v_ashrrev_i32_e32 v184, 6, v147
	v_lshl_add_u64 v[144:145], s[14:15], 0, v[144:145]
	v_ashrrev_i32_e32 v185, 31, v184
	v_lshl_add_u64 v[144:145], v[144:145], 0, v[2:3]
	v_lshlrev_b64 v[188:189], 9, v[184:185]
	v_add_co_u32_e32 v182, vcc, s49, v144
	v_lshl_add_u64 v[188:189], s[14:15], 0, v[188:189]
	s_nop 0
	v_addc_co_u32_e32 v183, vcc, 0, v145, vcc
	v_lshl_add_u64 v[188:189], v[188:189], 0, v[2:3]
	v_add_co_u32_e32 v190, vcc, s49, v188
	v_mad_u64_u32 v[146:147], s[20:21], v146, s52, v[4:5]
	s_nop 0
	v_addc_co_u32_e32 v191, vcc, 0, v189, vcc
	global_load_dwordx2 v[192:193], v[144:145], off nt
	s_nop 0
	global_load_dwordx2 v[182:183], v[182:183], off nt
	s_nop 0
	global_load_dwordx2 v[188:189], v[188:189], off nt
	s_nop 0
	global_load_dwordx2 v[190:191], v[190:191], off nt
	v_lshl_add_u32 v146, v146, 2, 0
	v_and_b32_e32 v137, 48, v187
	s_waitcnt vmcnt(15)
; __device__ __forceinline__ float bflo(unsigned v) { return __uint_as_float(v << 16); }
; __device__ __forceinline__ float bfhi(unsigned v) { return __uint_as_float(v & 0xffff0000u); }
; __device__ __forceinline__ void phase4(const Params& p, char* shm) {
;     ...
;         for (int i = 0; i < 8; ++i) { const int id = tid + (b8 * 8 + i) * NTHR, row = id >> 6, c = id & 63;
;           f32x4 rt = { bflo(ga[i][0]) * __builtin_amdgcn_rcpf(bflo(gb[i][0])), bfhi(ga[i][0]) * __builtin_amdgcn_rcpf(bfhi(gb[i][0])),
;                        bflo(ga[i][1]) * __builtin_amdgcn_rcpf(bflo(gb[i][1])), bfhi(ga[i][1]) * __builtin_amdgcn_rcpf(bfhi(gb[i][1])) };
;           *reinterpret_cast<f32x4*>(shm + (row * CF_LD + c * 4) * 4) = rt; }
	v_lshlrev_b32_e32 v194, 16, v148
	s_waitcnt vmcnt(14)
	v_lshlrev_b32_e32 v144, 16, v142
	v_and_b32_e32 v142, 0xffff0000, v142
	v_rcp_f32_e32 v145, v142
	v_lshlrev_b32_e32 v142, 16, v143
	v_rcp_f32_e32 v144, v144
	v_rcp_f32_e32 v196, v142
	v_and_b32_e32 v142, 0xffff0000, v143
	v_rcp_f32_e32 v197, v142
	v_and_b32_e32 v195, 0xffff0000, v148
	v_pk_mul_f32 v[142:143], v[144:145], v[194:195]
	v_lshlrev_b32_e32 v144, 16, v149
	v_and_b32_e32 v145, 0xffff0000, v149
	v_pk_mul_f32 v[144:145], v[196:197], v[144:145]
	ds_write_b128 v146, v[142:145]
	s_waitcnt vmcnt(12)
	v_lshlrev_b32_e32 v142, 16, v152
	v_and_b32_e32 v143, 0xffff0000, v152
	v_rcp_f32_e32 v142, v142
	v_rcp_f32_e32 v143, v143
	v_lshlrev_b32_e32 v146, 16, v153
	v_and_b32_e32 v147, 0xffff0000, v153
	v_rcp_f32_e32 v146, v146
	v_rcp_f32_e32 v147, v147
	v_lshlrev_b32_e32 v144, 16, v154
	v_and_b32_e32 v145, 0xffff0000, v154
	v_pk_mul_f32 v[142:143], v[142:143], v[144:145]
	v_lshlrev_b32_e32 v144, 16, v155
	v_and_b32_e32 v145, 0xffff0000, v155
	v_pk_mul_f32 v[144:145], v[146:147], v[144:145]
	v_mad_u64_u32 v[146:147], s[20:21], v150, s52, v[4:5]
	v_lshl_add_u32 v146, v146, 2, 0
	ds_write_b128 v146, v[142:145]
	s_waitcnt vmcnt(10)
	v_lshlrev_b32_e32 v142, 16, v158
	v_and_b32_e32 v143, 0xffff0000, v158
	v_rcp_f32_e32 v142, v142
	v_rcp_f32_e32 v143, v143
	v_lshlrev_b32_e32 v146, 16, v159
	v_and_b32_e32 v147, 0xffff0000, v159
	v_rcp_f32_e32 v146, v146
	v_rcp_f32_e32 v147, v147
	v_lshlrev_b32_e32 v144, 16, v166
	v_and_b32_e32 v145, 0xffff0000, v166
	v_pk_mul_f32 v[142:143], v[142:143], v[144:145]
	v_lshlrev_b32_e32 v144, 16, v167
	v_and_b32_e32 v145, 0xffff0000, v167
	v_pk_mul_f32 v[144:145], v[146:147], v[144:145]
	v_mad_u64_u32 v[146:147], s[20:21], v156, s52, v[4:5]
	v_lshl_add_u32 v146, v146, 2, 0
	ds_write_b128 v146, v[142:145]
	s_waitcnt vmcnt(8)
	v_lshlrev_b32_e32 v142, 16, v164
	v_and_b32_e32 v143, 0xffff0000, v164
	v_rcp_f32_e32 v142, v142
	v_rcp_f32_e32 v143, v143
	v_lshlrev_b32_e32 v146, 16, v165
	v_and_b32_e32 v147, 0xffff0000, v165
	v_rcp_f32_e32 v146, v146
	v_rcp_f32_e32 v147, v147
	v_lshlrev_b32_e32 v144, 16, v162
	v_and_b32_e32 v145, 0xffff0000, v162
	v_pk_mul_f32 v[142:143], v[142:143], v[144:145]
	v_lshlrev_b32_e32 v144, 16, v163
	v_and_b32_e32 v145, 0xffff0000, v163
	v_pk_mul_f32 v[144:145], v[146:147], v[144:145]
	v_mad_u64_u32 v[146:147], s[20:21], v160, s52, v[4:5]
	v_lshl_add_u32 v146, v146, 2, 0
	ds_write_b128 v146, v[142:145]
	s_waitcnt vmcnt(6)
	v_lshlrev_b32_e32 v142, 16, v170
	v_and_b32_e32 v143, 0xffff0000, v170
	v_rcp_f32_e32 v142, v142
	v_rcp_f32_e32 v143, v143
	v_lshlrev_b32_e32 v146, 16, v171
	v_and_b32_e32 v147, 0xffff0000, v171
	v_rcp_f32_e32 v146, v146
	v_rcp_f32_e32 v147, v147
	v_lshlrev_b32_e32 v144, 16, v178
	v_and_b32_e32 v145, 0xffff0000, v178
	v_pk_mul_f32 v[142:143], v[142:143], v[144:145]
	v_lshlrev_b32_e32 v144, 16, v179
	v_and_b32_e32 v145, 0xffff0000, v179
	v_pk_mul_f32 v[144:145], v[146:147], v[144:145]
	v_mad_u64_u32 v[146:147], s[20:21], v168, s52, v[4:5]
	v_lshl_add_u32 v146, v146, 2, 0
	ds_write_b128 v146, v[142:145]
	s_waitcnt vmcnt(4)
	v_lshlrev_b32_e32 v142, 16, v176
	v_and_b32_e32 v143, 0xffff0000, v176
	v_rcp_f32_e32 v142, v142
	v_rcp_f32_e32 v143, v143
	v_lshlrev_b32_e32 v146, 16, v177
	v_and_b32_e32 v147, 0xffff0000, v177
	v_rcp_f32_e32 v146, v146
	v_rcp_f32_e32 v147, v147
	v_lshlrev_b32_e32 v144, 16, v174
	v_and_b32_e32 v145, 0xffff0000, v174
	v_pk_mul_f32 v[142:143], v[142:143], v[144:145]
	v_lshlrev_b32_e32 v144, 16, v175
	v_and_b32_e32 v145, 0xffff0000, v175
	v_pk_mul_f32 v[144:145], v[146:147], v[144:145]
	v_mad_u64_u32 v[146:147], s[20:21], v172, s52, v[4:5]
	v_lshl_add_u32 v146, v146, 2, 0
	ds_write_b128 v146, v[142:145]
	s_waitcnt vmcnt(2)
	v_lshlrev_b32_e32 v142, 16, v182
	v_and_b32_e32 v143, 0xffff0000, v182
	v_rcp_f32_e32 v142, v142
	v_rcp_f32_e32 v143, v143
	v_lshlrev_b32_e32 v146, 16, v183
	v_and_b32_e32 v147, 0xffff0000, v183
	v_rcp_f32_e32 v146, v146
	v_rcp_f32_e32 v147, v147
	v_lshlrev_b32_e32 v144, 16, v192
	v_and_b32_e32 v145, 0xffff0000, v192
	v_pk_mul_f32 v[142:143], v[142:143], v[144:145]
	v_lshlrev_b32_e32 v144, 16, v193
	v_and_b32_e32 v145, 0xffff0000, v193
	v_pk_mul_f32 v[144:145], v[146:147], v[144:145]
	v_mad_u64_u32 v[146:147], s[20:21], v180, s52, v[4:5]
	v_lshl_add_u32 v146, v146, 2, 0
	ds_write_b128 v146, v[142:145]
	s_waitcnt vmcnt(0)
; __device__ __forceinline__ float bflo(unsigned v) { return __uint_as_float(v << 16); }
; __device__ __forceinline__ float bfhi(unsigned v) { return __uint_as_float(v & 0xffff0000u); }
; __device__ __forceinline__ void phase4(const Params& p, char* shm) {
;     ...
;         for (int i = 0; i < 8; ++i) { const int id = tid + (b8 * 8 + i) * NTHR, row = id >> 6, c = id & 63;
;           ga[i] = *reinterpret_cast<const u32x2*>(gsrc + (size_t)row * 4096 + c * 4);
;           gb[i] = *reinterpret_cast<const u32x2*>(gsrc + (size_t)row * 4096 + 2048 + c * 4); }
;     ...
;         for (int i = 0; i < 8; ++i) { const int id = tid + (b8 * 8 + i) * NTHR, row = id >> 6, c = id & 63;
;           f32x4 rt = { bflo(ga[i][0]) * __builtin_amdgcn_rcpf(bflo(gb[i][0])), bfhi(ga[i][0]) * __builtin_amdgcn_rcpf(bfhi(gb[i][0])),
;                        bflo(ga[i][1]) * __builtin_amdgcn_rcpf(bflo(gb[i][1])), bfhi(ga[i][1]) * __builtin_amdgcn_rcpf(bfhi(gb[i][1])) };
;           *reinterpret_cast<f32x4*>(shm + (row * CF_LD + c * 4) * 4) = rt; }
;     ...
; #pragma unroll
;       for (int bj = 0; bj < 2; ++bj)
; #pragma unroll
;         for (int m = 0; m < 4; ++m)
; #pragma unroll
;           for (int n = 0; n < 2; ++n) acc[ai][bj][m][n] *= *(const f32x4*)(cfb + CF_OFF(bj, m, n));
	v_lshlrev_b32_e32 v142, 16, v190
	v_and_b32_e32 v143, 0xffff0000, v190
	v_rcp_f32_e32 v142, v142
	v_rcp_f32_e32 v143, v143
	v_lshlrev_b32_e32 v146, 16, v191
	v_and_b32_e32 v147, 0xffff0000, v191
	v_rcp_f32_e32 v146, v146
	v_rcp_f32_e32 v147, v147
	v_lshlrev_b32_e32 v144, 16, v188
	v_and_b32_e32 v145, 0xffff0000, v188
	v_pk_mul_f32 v[142:143], v[142:143], v[144:145]
	v_lshlrev_b32_e32 v144, 16, v189
	v_and_b32_e32 v145, 0xffff0000, v189
	v_pk_mul_f32 v[144:145], v[146:147], v[144:145]
	v_mad_u64_u32 v[146:147], s[20:21], v184, s52, v[4:5]
	v_lshl_add_u32 v146, v146, 2, 0
	ds_write_b128 v146, v[142:145]
	v_add_u32_e32 v142, 0x1000, v187
	v_ashrrev_i32_e32 v146, 6, v142
	v_ashrrev_i32_e32 v147, 31, v146
	v_lshlrev_b64 v[142:143], 9, v[146:147]
	v_lshl_add_u64 v[142:143], s[14:15], 0, v[142:143]
	v_lshl_add_u64 v[142:143], v[142:143], 0, v[2:3]
	v_add_co_u32_e32 v144, vcc, s49, v142
	v_add_u32_e32 v147, 0x1600, v187
	s_nop 0
	v_addc_co_u32_e32 v145, vcc, 0, v143, vcc
	global_load_dwordx2 v[148:149], v[142:143], off nt
	s_nop 0
	global_load_dwordx2 v[142:143], v[144:145], off nt
	v_add_u32_e32 v144, 0x1200, v187
	v_ashrrev_i32_e32 v150, 6, v144
	v_ashrrev_i32_e32 v151, 31, v150
	v_lshlrev_b64 v[144:145], 9, v[150:151]
	v_lshl_add_u64 v[144:145], s[14:15], 0, v[144:145]
	v_lshl_add_u64 v[144:145], v[144:145], 0, v[2:3]
	v_add_co_u32_e32 v152, vcc, s49, v144
	v_ashrrev_i32_e32 v160, 6, v147
	s_nop 0
	v_addc_co_u32_e32 v153, vcc, 0, v145, vcc
	global_load_dwordx2 v[154:155], v[144:145], off nt
	s_nop 0
	global_load_dwordx2 v[152:153], v[152:153], off nt
	v_add_u32_e32 v144, 0x1400, v187
	v_ashrrev_i32_e32 v156, 6, v144
	v_ashrrev_i32_e32 v157, 31, v156
	v_lshlrev_b64 v[144:145], 9, v[156:157]
	v_lshl_add_u64 v[144:145], s[14:15], 0, v[144:145]
	v_ashrrev_i32_e32 v161, 31, v160
	v_lshl_add_u64 v[144:145], v[144:145], 0, v[2:3]
	v_lshlrev_b64 v[162:163], 9, v[160:161]
	v_add_co_u32_e32 v158, vcc, s49, v144
	v_lshl_add_u64 v[162:163], s[14:15], 0, v[162:163]
	s_nop 0
	v_addc_co_u32_e32 v159, vcc, 0, v145, vcc
	v_lshl_add_u64 v[162:163], v[162:163], 0, v[2:3]
	v_add_co_u32_e32 v164, vcc, s49, v162
	v_add_u32_e32 v147, 0x1a00, v187
	s_nop 0
	v_addc_co_u32_e32 v165, vcc, 0, v163, vcc
	global_load_dwordx2 v[166:167], v[144:145], off nt
	s_nop 0
	global_load_dwordx2 v[158:159], v[158:159], off nt
	s_nop 0
	global_load_dwordx2 v[162:163], v[162:163], off nt
	s_nop 0
	global_load_dwordx2 v[164:165], v[164:165], off nt
	v_add_u32_e32 v144, 0x1800, v187
	v_ashrrev_i32_e32 v168, 6, v144
	v_ashrrev_i32_e32 v169, 31, v168
	v_lshlrev_b64 v[144:145], 9, v[168:169]
	v_ashrrev_i32_e32 v172, 6, v147
	v_lshl_add_u64 v[144:145], s[14:15], 0, v[144:145]
	v_ashrrev_i32_e32 v173, 31, v172
	v_lshl_add_u64 v[144:145], v[144:145], 0, v[2:3]
	v_lshlrev_b64 v[174:175], 9, v[172:173]
	v_add_co_u32_e32 v170, vcc, s49, v144
	v_lshl_add_u64 v[174:175], s[14:15], 0, v[174:175]
	s_nop 0
	v_addc_co_u32_e32 v171, vcc, 0, v145, vcc
	v_lshl_add_u64 v[174:175], v[174:175], 0, v[2:3]
	v_add_co_u32_e32 v176, vcc, s49, v174
	v_add_u32_e32 v147, 0x1e00, v187
	s_nop 0
	v_addc_co_u32_e32 v177, vcc, 0, v175, vcc
	global_load_dwordx2 v[178:179], v[144:145], off nt
	s_nop 0
	global_load_dwordx2 v[170:171], v[170:171], off nt
	s_nop 0
	global_load_dwordx2 v[174:175], v[174:175], off nt
	s_nop 0
	global_load_dwordx2 v[176:177], v[176:177], off nt
	v_add_u32_e32 v144, 0x1c00, v187
	v_ashrrev_i32_e32 v180, 6, v144
	v_ashrrev_i32_e32 v181, 31, v180
	v_lshlrev_b64 v[144:145], 9, v[180:181]
	v_ashrrev_i32_e32 v184, 6, v147
	v_lshl_add_u64 v[144:145], s[14:15], 0, v[144:145]
	v_ashrrev_i32_e32 v185, 31, v184
	v_lshl_add_u64 v[144:145], v[144:145], 0, v[2:3]
	v_lshlrev_b64 v[188:189], 9, v[184:185]
	v_add_co_u32_e32 v182, vcc, s49, v144
	v_lshl_add_u64 v[188:189], s[14:15], 0, v[188:189]
	s_nop 0
	v_addc_co_u32_e32 v183, vcc, 0, v145, vcc
	v_lshl_add_u64 v[188:189], v[188:189], 0, v[2:3]
	v_add_co_u32_e32 v190, vcc, s49, v188
	v_mad_u64_u32 v[146:147], s[20:21], v146, s52, v[4:5]
	s_nop 0
	v_addc_co_u32_e32 v191, vcc, 0, v189, vcc
	global_load_dwordx2 v[192:193], v[144:145], off nt
	s_nop 0
	global_load_dwordx2 v[182:183], v[182:183], off nt
	s_nop 0
	global_load_dwordx2 v[188:189], v[188:189], off nt
	s_nop 0
	global_load_dwordx2 v[190:191], v[190:191], off nt
	v_pk_mul_f32 v[74:75], v[74:75], v[134:135]
	v_pk_mul_f32 v[72:73], v[72:73], v[140:141]
	v_pk_mul_f32 v[70:71], v[70:71], v[138:139]
	s_waitcnt vmcnt(15)
	v_lshlrev_b32_e32 v194, 16, v148
	s_waitcnt vmcnt(14)
	v_lshlrev_b32_e32 v2, 16, v142
	v_rcp_f32_e32 v144, v2
	v_and_b32_e32 v2, 0xffff0000, v142
	v_rcp_f32_e32 v145, v2
	v_lshlrev_b32_e32 v2, 16, v143
	v_rcp_f32_e32 v196, v2
	v_and_b32_e32 v2, 0xffff0000, v143
	v_rcp_f32_e32 v197, v2
	v_and_b32_e32 v195, 0xffff0000, v148
	v_pk_mul_f32 v[142:143], v[144:145], v[194:195]
	v_lshlrev_b32_e32 v144, 16, v149
	v_and_b32_e32 v145, 0xffff0000, v149
	v_pk_mul_f32 v[144:145], v[196:197], v[144:145]
	v_lshl_add_u32 v2, v146, 2, 0
	ds_write_b128 v2, v[142:145]
	s_waitcnt vmcnt(12)
	v_lshlrev_b32_e32 v2, 16, v152
	v_rcp_f32_e32 v142, v2
	v_and_b32_e32 v2, 0xffff0000, v152
	v_rcp_f32_e32 v143, v2
	v_lshlrev_b32_e32 v2, 16, v153
	v_rcp_f32_e32 v146, v2
	v_and_b32_e32 v2, 0xffff0000, v153
	v_rcp_f32_e32 v147, v2
	v_lshlrev_b32_e32 v144, 16, v154
	v_and_b32_e32 v145, 0xffff0000, v154
	v_pk_mul_f32 v[142:143], v[142:143], v[144:145]
	v_lshlrev_b32_e32 v144, 16, v155
	v_and_b32_e32 v145, 0xffff0000, v155
	v_pk_mul_f32 v[144:145], v[146:147], v[144:145]
	v_mad_u64_u32 v[146:147], s[20:21], v150, s52, v[4:5]
	v_lshl_add_u32 v2, v146, 2, 0
	ds_write_b128 v2, v[142:145]
	s_waitcnt vmcnt(10)
; __device__ __forceinline__ float bflo(unsigned v) { return __uint_as_float(v << 16); }
; __device__ __forceinline__ float bfhi(unsigned v) { return __uint_as_float(v & 0xffff0000u); }
; __device__ __forceinline__ void phase4(const Params& p, char* shm) {
;     ...
;         for (int i = 0; i < 8; ++i) { const int id = tid + (b8 * 8 + i) * NTHR, row = id >> 6, c = id & 63;
;           f32x4 rt = { bflo(ga[i][0]) * __builtin_amdgcn_rcpf(bflo(gb[i][0])), bfhi(ga[i][0]) * __builtin_amdgcn_rcpf(bfhi(gb[i][0])),
;                        bflo(ga[i][1]) * __builtin_amdgcn_rcpf(bflo(gb[i][1])), bfhi(ga[i][1]) * __builtin_amdgcn_rcpf(bfhi(gb[i][1])) };
;           *reinterpret_cast<f32x4*>(shm + (row * CF_LD + c * 4) * 4) = rt; }
;       }
;       __syncthreads();
; #pragma unroll
;       for (int bj = 0; bj < 2; ++bj)
; #pragma unroll
;         for (int m = 0; m < 4; ++m)
; #pragma unroll
;           for (int n = 0; n < 2; ++n) acc[ai][bj][m][n] *= *(const f32x4*)(cfb + CF_OFF(bj, m, n));
;       __syncthreads();
	v_lshlrev_b32_e32 v2, 16, v158
	v_rcp_f32_e32 v142, v2
	v_and_b32_e32 v2, 0xffff0000, v158
	v_rcp_f32_e32 v143, v2
	v_lshlrev_b32_e32 v2, 16, v159
	v_rcp_f32_e32 v146, v2
	v_and_b32_e32 v2, 0xffff0000, v159
	v_rcp_f32_e32 v147, v2
	v_lshlrev_b32_e32 v144, 16, v166
	v_and_b32_e32 v145, 0xffff0000, v166
	v_pk_mul_f32 v[142:143], v[142:143], v[144:145]
	v_lshlrev_b32_e32 v144, 16, v167
	v_and_b32_e32 v145, 0xffff0000, v167
	v_pk_mul_f32 v[144:145], v[146:147], v[144:145]
	v_mad_u64_u32 v[146:147], s[20:21], v156, s52, v[4:5]
	v_lshl_add_u32 v2, v146, 2, 0
	ds_write_b128 v2, v[142:145]
	s_waitcnt vmcnt(8)
	v_lshlrev_b32_e32 v2, 16, v164
	v_rcp_f32_e32 v142, v2
	v_and_b32_e32 v2, 0xffff0000, v164
	v_rcp_f32_e32 v143, v2
	v_lshlrev_b32_e32 v2, 16, v165
	v_rcp_f32_e32 v146, v2
	v_and_b32_e32 v2, 0xffff0000, v165
	v_rcp_f32_e32 v147, v2
	v_lshlrev_b32_e32 v144, 16, v162
	v_and_b32_e32 v145, 0xffff0000, v162
	v_pk_mul_f32 v[142:143], v[142:143], v[144:145]
	v_lshlrev_b32_e32 v144, 16, v163
	v_and_b32_e32 v145, 0xffff0000, v163
	v_pk_mul_f32 v[144:145], v[146:147], v[144:145]
	v_mad_u64_u32 v[146:147], s[20:21], v160, s52, v[4:5]
	v_lshl_add_u32 v2, v146, 2, 0
	ds_write_b128 v2, v[142:145]
	s_waitcnt vmcnt(6)
	v_lshlrev_b32_e32 v2, 16, v170
	v_rcp_f32_e32 v142, v2
	v_and_b32_e32 v2, 0xffff0000, v170
	v_rcp_f32_e32 v143, v2
	v_lshlrev_b32_e32 v2, 16, v171
	v_rcp_f32_e32 v146, v2
	v_and_b32_e32 v2, 0xffff0000, v171
	v_rcp_f32_e32 v147, v2
	v_lshlrev_b32_e32 v144, 16, v178
	v_and_b32_e32 v145, 0xffff0000, v178
	v_pk_mul_f32 v[142:143], v[142:143], v[144:145]
	v_lshlrev_b32_e32 v144, 16, v179
	v_and_b32_e32 v145, 0xffff0000, v179
	v_pk_mul_f32 v[144:145], v[146:147], v[144:145]
	v_mad_u64_u32 v[146:147], s[20:21], v168, s52, v[4:5]
	v_lshl_add_u32 v2, v146, 2, 0
	ds_write_b128 v2, v[142:145]
	s_waitcnt vmcnt(4)
	v_lshlrev_b32_e32 v2, 16, v176
	v_rcp_f32_e32 v142, v2
	v_and_b32_e32 v2, 0xffff0000, v176
	v_rcp_f32_e32 v143, v2
	v_lshlrev_b32_e32 v2, 16, v177
	v_rcp_f32_e32 v146, v2
	v_and_b32_e32 v2, 0xffff0000, v177
	v_rcp_f32_e32 v147, v2
	v_lshlrev_b32_e32 v144, 16, v174
	v_and_b32_e32 v145, 0xffff0000, v174
	v_pk_mul_f32 v[142:143], v[142:143], v[144:145]
	v_lshlrev_b32_e32 v144, 16, v175
	v_and_b32_e32 v145, 0xffff0000, v175
	v_pk_mul_f32 v[144:145], v[146:147], v[144:145]
	v_mad_u64_u32 v[146:147], s[20:21], v172, s52, v[4:5]
	v_lshl_add_u32 v2, v146, 2, 0
	ds_write_b128 v2, v[142:145]
	s_waitcnt vmcnt(2)
	v_lshlrev_b32_e32 v2, 16, v182
	v_rcp_f32_e32 v142, v2
	v_and_b32_e32 v2, 0xffff0000, v182
	v_rcp_f32_e32 v143, v2
	v_lshlrev_b32_e32 v2, 16, v183
	v_rcp_f32_e32 v146, v2
	v_and_b32_e32 v2, 0xffff0000, v183
	v_rcp_f32_e32 v147, v2
	v_lshlrev_b32_e32 v144, 16, v192
	v_and_b32_e32 v145, 0xffff0000, v192
	v_pk_mul_f32 v[142:143], v[142:143], v[144:145]
	v_lshlrev_b32_e32 v144, 16, v193
	v_and_b32_e32 v145, 0xffff0000, v193
	v_pk_mul_f32 v[144:145], v[146:147], v[144:145]
	v_mad_u64_u32 v[146:147], s[20:21], v180, s52, v[4:5]
	v_lshl_add_u32 v2, v146, 2, 0
	ds_write_b128 v2, v[142:145]
	s_waitcnt vmcnt(0)
	v_lshlrev_b32_e32 v2, 16, v190
	v_rcp_f32_e32 v142, v2
	v_and_b32_e32 v2, 0xffff0000, v190
	v_rcp_f32_e32 v143, v2
	v_lshlrev_b32_e32 v2, 16, v191
	v_rcp_f32_e32 v146, v2
	v_and_b32_e32 v2, 0xffff0000, v191
	v_rcp_f32_e32 v147, v2
	v_lshlrev_b32_e32 v144, 16, v188
	v_and_b32_e32 v145, 0xffff0000, v188
	v_pk_mul_f32 v[142:143], v[142:143], v[144:145]
	v_lshlrev_b32_e32 v144, 16, v189
	v_and_b32_e32 v145, 0xffff0000, v189
	v_pk_mul_f32 v[144:145], v[146:147], v[144:145]
	v_mad_u64_u32 v[146:147], s[20:21], v184, s52, v[4:5]
	v_lshl_add_u32 v2, v146, 2, 0
	ds_write_b128 v2, v[142:145]
	v_add_lshl_u32 v2, v5, v136, 2
	v_add3_u32 v2, 0, v137, v2
	s_waitcnt lgkmcnt(0)
	s_barrier
	ds_read_b128 v[142:145], v2
	ds_read_b128 v[134:137], v2 offset:64
	ds_read_b128 v[138:141], v2 offset:16640
	s_waitcnt lgkmcnt(2)
	v_pk_mul_f32 v[68:69], v[68:69], v[144:145]
	v_pk_mul_f32 v[66:67], v[66:67], v[142:143]
	ds_read_b128 v[142:145], v2 offset:16704
	s_waitcnt lgkmcnt(2)
	v_pk_mul_f32 v[64:65], v[64:65], v[136:137]
	v_pk_mul_f32 v[62:63], v[62:63], v[134:135]
	s_waitcnt lgkmcnt(1)
	v_pk_mul_f32 v[60:61], v[60:61], v[140:141]
	ds_read_b128 v[134:137], v2 offset:33280
	v_pk_mul_f32 v[58:59], v[58:59], v[138:139]
	s_waitcnt lgkmcnt(1)
	v_pk_mul_f32 v[56:57], v[56:57], v[144:145]
	ds_read_b128 v[138:141], v2 offset:33344
	v_pk_mul_f32 v[54:55], v[54:55], v[142:143]
	ds_read_b128 v[142:145], v2 offset:49920
	s_waitcnt lgkmcnt(2)
	v_pk_mul_f32 v[52:53], v[52:53], v[136:137]
	v_pk_mul_f32 v[50:51], v[50:51], v[134:135]
	s_waitcnt lgkmcnt(1)
	v_pk_mul_f32 v[48:49], v[48:49], v[140:141]
	ds_read_b128 v[134:137], v2 offset:49984
	v_pk_mul_f32 v[46:47], v[46:47], v[138:139]
	s_waitcnt lgkmcnt(1)
	v_pk_mul_f32 v[44:45], v[44:45], v[144:145]
	ds_read_b128 v[138:141], v2 offset:512
	v_pk_mul_f32 v[42:43], v[42:43], v[142:143]
	ds_read_b128 v[142:145], v2 offset:576
	s_waitcnt lgkmcnt(2)
	v_pk_mul_f32 v[40:41], v[40:41], v[136:137]
	v_pk_mul_f32 v[38:39], v[38:39], v[134:135]
	s_waitcnt lgkmcnt(1)
	v_pk_mul_f32 v[36:37], v[36:37], v[140:141]
	ds_read_b128 v[134:137], v2 offset:17152
	v_pk_mul_f32 v[34:35], v[34:35], v[138:139]
	s_waitcnt lgkmcnt(1)
	v_pk_mul_f32 v[32:33], v[32:33], v[144:145]
	ds_read_b128 v[138:141], v2 offset:17216
	v_pk_mul_f32 v[30:31], v[30:31], v[142:143]
	ds_read_b128 v[142:145], v2 offset:33792
	s_waitcnt lgkmcnt(2)
	v_pk_mul_f32 v[28:29], v[28:29], v[136:137]
	v_pk_mul_f32 v[26:27], v[26:27], v[134:135]
	s_waitcnt lgkmcnt(1)
	v_pk_mul_f32 v[24:25], v[24:25], v[140:141]
	v_pk_mul_f32 v[22:23], v[22:23], v[138:139]
	ds_read_b128 v[134:137], v2 offset:33856
	s_waitcnt lgkmcnt(1)
	v_pk_mul_f32 v[20:21], v[20:21], v[144:145]
	ds_read_b128 v[138:141], v2 offset:50432
	v_pk_mul_f32 v[18:19], v[18:19], v[142:143]
	ds_read_b128 v[142:145], v2 offset:50496
	s_waitcnt lgkmcnt(2)
	v_pk_mul_f32 v[16:17], v[16:17], v[136:137]
	v_pk_mul_f32 v[14:15], v[14:15], v[134:135]
	s_waitcnt lgkmcnt(1)
	v_pk_mul_f32 v[12:13], v[12:13], v[140:141]
	v_pk_mul_f32 v[10:11], v[10:11], v[138:139]
	s_waitcnt lgkmcnt(0)
	v_pk_mul_f32 v[8:9], v[8:9], v[144:145]
	v_pk_mul_f32 v[6:7], v[6:7], v[142:143]
	s_barrier
	s_branch .LBB0_450
; __device__ __forceinline__ void phase4(const Params& p, char* shm) {
;     ...
;     { const u16* gsrc = Gates + brow * 4096 + 2048 + bcol;
; #pragma unroll
;       for (int b8 = 0; b8 < 2; ++b8) {
;         u32x4 gv[8];
; #pragma unroll
;         for (int i = 0; i < 8; ++i) { const int id = tid + (b8 * 8 + i) * NTHR, row = id >> 5, c = id & 31;
;           gv[i] = *reinterpret_cast<const u32x4*>(gsrc + (size_t)row * 4096 + c * 8); }
; #pragma unroll
;         for (int i = 0; i < 8; ++i) { const int id = tid + (b8 * 8 + i) * NTHR, row = id >> 5, c = id & 31;
;           *reinterpret_cast<u32x4*>(shm + (row * CT_LD + c * 8) * 2) = gv[i]; }
;       }
;     }
;     __syncthreads();
.LBB0_459:
	v_mov_b32_e32 v5, v1
	s_add_u32 s8, s24, s8
	s_addc_u32 s9, s25, s9
	s_lshl_b32 s12, s63, 1
	v_lshlrev_b32_e32 v2, 3, v5
	s_lshl_b32 s98, s63, 9
	s_add_u32 s8, s8, s98
	v_and_b32_e32 v4, 0xf8, v2
	s_addc_u32 s9, s9, 0
	v_lshlrev_b32_e32 v2, 1, v4
	v_lshl_add_u64 v[134:135], s[8:9], 0, v[2:3]
	v_add_u32_e32 v2, 0x200, v5
	v_ashrrev_i32_e32 v200, 5, v5
	v_ashrrev_i32_e32 v202, 5, v2
	v_ashrrev_i32_e32 v201, 31, v200
	v_ashrrev_i32_e32 v203, 31, v202
	v_add_u32_e32 v2, 0x400, v5
	v_lshl_add_u64 v[196:197], v[134:135], 0, s[4:5]
	v_lshlrev_b64 v[134:135], 9, v[200:201]
	v_lshlrev_b64 v[136:137], 9, v[202:203]
	v_ashrrev_i32_e32 v204, 5, v2
	v_add_u32_e32 v2, 0x600, v5
	v_lshl_add_u64 v[134:135], v[196:197], 0, v[134:135]
	v_lshl_add_u64 v[138:139], v[196:197], 0, v[136:137]
	v_ashrrev_i32_e32 v206, 5, v2
	v_add_u32_e32 v2, 0x800, v5
	global_load_dwordx4 v[134:137], v[134:135], off nt
	s_nop 0
	global_load_dwordx4 v[138:141], v[138:139], off nt
	v_ashrrev_i32_e32 v205, 31, v204
	v_ashrrev_i32_e32 v207, 31, v206
	v_ashrrev_i32_e32 v208, 5, v2
	v_add_u32_e32 v2, 0xa00, v5
	v_lshlrev_b64 v[142:143], 9, v[204:205]
	v_lshlrev_b64 v[144:145], 9, v[206:207]
	v_ashrrev_i32_e32 v210, 5, v2
	v_add_u32_e32 v2, 0xc00, v5
	v_lshl_add_u64 v[142:143], v[196:197], 0, v[142:143]
	v_lshl_add_u64 v[146:147], v[196:197], 0, v[144:145]
	v_ashrrev_i32_e32 v209, 31, v208
	v_ashrrev_i32_e32 v211, 31, v210
	v_ashrrev_i32_e32 v212, 5, v2
	v_add_u32_e32 v2, 0xe00, v5
	global_load_dwordx4 v[142:145], v[142:143], off nt
	s_nop 0
	global_load_dwordx4 v[146:149], v[146:147], off nt
	v_lshlrev_b64 v[150:151], 9, v[208:209]
	v_lshlrev_b64 v[152:153], 9, v[210:211]
	v_ashrrev_i32_e32 v214, 5, v2
	v_add_u32_e32 v2, 0x1000, v5
	v_lshl_add_u64 v[150:151], v[196:197], 0, v[150:151]
	v_lshl_add_u64 v[154:155], v[196:197], 0, v[152:153]
	v_ashrrev_i32_e32 v213, 31, v212
	v_ashrrev_i32_e32 v215, 31, v214
	v_ashrrev_i32_e32 v216, 5, v2
	v_add_u32_e32 v2, 0x1200, v5
	global_load_dwordx4 v[150:153], v[150:151], off nt
	s_nop 0
	global_load_dwordx4 v[154:157], v[154:155], off nt
	v_lshlrev_b64 v[158:159], 9, v[212:213]
	v_lshlrev_b64 v[160:161], 9, v[214:215]
	v_ashrrev_i32_e32 v218, 5, v2
	v_add_u32_e32 v2, 0x1400, v5
	v_lshl_add_u64 v[158:159], v[196:197], 0, v[158:159]
	v_lshl_add_u64 v[162:163], v[196:197], 0, v[160:161]
	v_ashrrev_i32_e32 v217, 31, v216
	v_ashrrev_i32_e32 v219, 31, v218
	v_ashrrev_i32_e32 v220, 5, v2
	v_add_u32_e32 v2, 0x1600, v5
	global_load_dwordx4 v[158:161], v[158:159], off nt
	s_nop 0
	global_load_dwordx4 v[162:165], v[162:163], off nt
	v_lshlrev_b64 v[166:167], 9, v[216:217]
	v_lshlrev_b64 v[168:169], 9, v[218:219]
	v_ashrrev_i32_e32 v222, 5, v2
	v_add_u32_e32 v2, 0x1800, v5
	v_lshl_add_u64 v[166:167], v[196:197], 0, v[166:167]
	v_lshl_add_u64 v[170:171], v[196:197], 0, v[168:169]
	v_ashrrev_i32_e32 v221, 31, v220
	v_ashrrev_i32_e32 v223, 31, v222
	v_ashrrev_i32_e32 v224, 5, v2
	v_add_u32_e32 v2, 0x1a00, v5
	global_load_dwordx4 v[166:169], v[166:167], off nt
	s_nop 0
	global_load_dwordx4 v[170:173], v[170:171], off nt
	v_lshlrev_b64 v[174:175], 9, v[220:221]
	v_lshlrev_b64 v[176:177], 9, v[222:223]
	v_ashrrev_i32_e32 v226, 5, v2
	v_add_u32_e32 v2, 0x1c00, v5
	v_lshl_add_u64 v[174:175], v[196:197], 0, v[174:175]
	v_lshl_add_u64 v[178:179], v[196:197], 0, v[176:177]
	v_ashrrev_i32_e32 v225, 31, v224
	v_ashrrev_i32_e32 v227, 31, v226
	v_ashrrev_i32_e32 v228, 5, v2
	v_add_u32_e32 v2, 0x1e00, v5
	global_load_dwordx4 v[174:177], v[174:175], off nt
	s_nop 0
	global_load_dwordx4 v[178:181], v[178:179], off nt
	v_lshlrev_b64 v[182:183], 9, v[224:225]
	v_lshlrev_b64 v[184:185], 9, v[226:227]
	v_ashrrev_i32_e32 v229, 31, v228
	v_ashrrev_i32_e32 v230, 5, v2
	v_lshl_add_u64 v[182:183], v[196:197], 0, v[182:183]
	v_lshl_add_u64 v[188:189], v[196:197], 0, v[184:185]
	v_lshlrev_b64 v[192:193], 9, v[228:229]
	v_ashrrev_i32_e32 v231, 31, v230
	global_load_dwordx4 v[182:185], v[182:183], off nt
	s_nop 0
	global_load_dwordx4 v[188:191], v[188:189], off nt
	v_lshl_add_u64 v[192:193], v[196:197], 0, v[192:193]
	v_lshlrev_b64 v[198:199], 9, v[230:231]
	global_load_dwordx4 v[192:195], v[192:193], off nt
	v_lshl_add_u64 v[196:197], v[196:197], 0, v[198:199]
	global_load_dwordx4 v[196:199], v[196:197], off nt
	v_and_b32_e32 v2, 15, v5
	v_lshrrev_b32_e32 v187, 2, v5
	v_and_or_b32 v201, v187, s54, v2
	v_lshrrev_b32_e32 v2, 1, v5
	v_and_b32_e32 v2, 0x60, v2
	v_and_or_b32 v2, v187, 12, v2
	v_mad_u64_u32 v[232:233], s[8:9], v201, s55, v[2:3]
	v_mad_u64_u32 v[200:201], s[8:9], v200, s55, v[4:5]
	v_lshl_add_u32 v2, v200, 1, 0
	s_waitcnt vmcnt(15)
	ds_write_b128 v2, v[134:137]
	v_mad_u64_u32 v[134:135], s[8:9], v202, s55, v[4:5]
	v_lshl_add_u32 v2, v134, 1, 0
	v_mad_u64_u32 v[134:135], s[8:9], v204, s55, v[4:5]
	s_waitcnt vmcnt(14)
	ds_write_b128 v2, v[138:141]
	v_lshl_add_u32 v2, v134, 1, 0
	v_mad_u64_u32 v[134:135], s[8:9], v206, s55, v[4:5]
	s_waitcnt vmcnt(13)
	ds_write_b128 v2, v[142:145]
	v_lshl_add_u32 v2, v134, 1, 0
	v_mad_u64_u32 v[134:135], s[8:9], v208, s55, v[4:5]
	s_waitcnt vmcnt(12)
	ds_write_b128 v2, v[146:149]
	v_lshl_add_u32 v2, v134, 1, 0
	v_mad_u64_u32 v[134:135], s[8:9], v210, s55, v[4:5]
	s_waitcnt vmcnt(11)
	ds_write_b128 v2, v[150:153]
	v_lshl_add_u32 v2, v134, 1, 0
	v_mad_u64_u32 v[134:135], s[8:9], v212, s55, v[4:5]
	s_waitcnt vmcnt(10)
	ds_write_b128 v2, v[154:157]
	v_lshl_add_u32 v2, v134, 1, 0
	v_mad_u64_u32 v[134:135], s[8:9], v214, s55, v[4:5]
	s_waitcnt vmcnt(9)
	ds_write_b128 v2, v[158:161]
	v_lshl_add_u32 v2, v134, 1, 0
	v_mad_u64_u32 v[134:135], s[8:9], v216, s55, v[4:5]
	s_waitcnt vmcnt(8)
	ds_write_b128 v2, v[162:165]
	v_lshl_add_u32 v2, v134, 1, 0
	v_mad_u64_u32 v[134:135], s[8:9], v218, s55, v[4:5]
	s_waitcnt vmcnt(7)
	ds_write_b128 v2, v[166:169]
	v_lshl_add_u32 v2, v134, 1, 0
	v_mad_u64_u32 v[134:135], s[8:9], v220, s55, v[4:5]
	s_waitcnt vmcnt(6)
	ds_write_b128 v2, v[170:173]
	v_lshl_add_u32 v2, v134, 1, 0
	v_mad_u64_u32 v[134:135], s[8:9], v222, s55, v[4:5]
	s_waitcnt vmcnt(5)
	ds_write_b128 v2, v[174:177]
	v_lshl_add_u32 v2, v134, 1, 0
	v_mad_u64_u32 v[134:135], s[8:9], v224, s55, v[4:5]
	s_waitcnt vmcnt(4)
	ds_write_b128 v2, v[178:181]
	v_lshl_add_u32 v2, v134, 1, 0
	v_mad_u64_u32 v[134:135], s[8:9], v226, s55, v[4:5]
	s_waitcnt vmcnt(3)
	ds_write_b128 v2, v[182:185]
	v_lshl_add_u32 v2, v134, 1, 0
	v_mad_u64_u32 v[134:135], s[8:9], v228, s55, v[4:5]
	s_waitcnt vmcnt(2)
	ds_write_b128 v2, v[188:191]
	v_lshl_add_u32 v2, v134, 1, 0
	v_mad_u64_u32 v[4:5], s[8:9], v230, s55, v[4:5]
	s_waitcnt vmcnt(1)
	ds_write_b128 v2, v[192:195]
	v_lshl_add_u32 v2, v4, 1, 0
	s_waitcnt vmcnt(0)
	ds_write_b128 v2, v[196:199]
	v_lshl_add_u32 v2, v232, 1, 0
	s_waitcnt lgkmcnt(0)
	s_barrier
; __device__ __forceinline__ float bflo(unsigned v) { return __uint_as_float(v << 16); }
; __device__ __forceinline__ float bfhi(unsigned v) { return __uint_as_float(v & 0xffff0000u); }
; #define FOR_FRAG(ai, bj, m, n) _Pragma("unroll") for (int ai = 0; ai < 2; ++ai) _Pragma("unroll") for (int bj = 0; bj < 2; ++bj) \
;   _Pragma("unroll") for (int m = 0; m < 4; ++m) _Pragma("unroll") for (int n = 0; n < 2; ++n)
; __device__ __forceinline__ u32x2 pack4(float a, float b, float c, float d) { return u32x2{cvtpk(a, b), cvtpk(c, d)}; }
; __device__ __forceinline__ void phase4(const Params& p, char* shm) {
;     ...
;     FOR_FRAG(ai, bj, m, n) { u32x2* q = (u32x2*)(ctb + CT_OFF(ai, bj, m, n)); const u32x2 g = *q; const f32x4 v = acc[ai][bj][m][n];
;       *q = pack4(v[0] * bflo(g[0]), v[1] * bfhi(g[0]), v[2] * bflo(g[1]), v[3] * bfhi(g[1])); }
	ds_read_b64 v[4:5], v2
	s_waitcnt lgkmcnt(0)
	v_lshlrev_b32_e32 v134, 16, v4
	v_and_b32_e32 v4, 0xffff0000, v4
	v_mul_f32_e32 v4, v131, v4
	v_lshlrev_b32_e32 v131, 16, v5
	v_and_b32_e32 v5, 0xffff0000, v5
	v_mul_f32_e32 v130, v130, v134
	v_mul_f32_e32 v131, v132, v131
	v_mul_f32_e32 v5, v133, v5
	s_nop 0
	v_cvt_pk_bf16_f32 v4, v130, v4
	s_nop 0
	v_cvt_pk_bf16_f32 v5, v131, v5
	ds_read_b64 v[130:131], v2 offset:32
	ds_write_b64 v2, v[4:5]
	s_waitcnt lgkmcnt(1)
	v_lshlrev_b32_e32 v4, 16, v130
	v_and_b32_e32 v5, 0xffff0000, v130
	v_mul_f32_e32 v4, v126, v4
	v_mul_f32_e32 v5, v127, v5
	v_lshlrev_b32_e32 v126, 16, v131
	v_and_b32_e32 v127, 0xffff0000, v131
	v_mul_f32_e32 v126, v128, v126
	v_mul_f32_e32 v127, v129, v127
	s_nop 0
	v_cvt_pk_bf16_f32 v4, v4, v5
	s_nop 0
	v_cvt_pk_bf16_f32 v5, v126, v127
	ds_read_b64 v[126:127], v2 offset:8448
	ds_write_b64 v2, v[4:5] offset:32
	s_waitcnt lgkmcnt(1)
	v_lshlrev_b32_e32 v4, 16, v126
	v_and_b32_e32 v5, 0xffff0000, v126
	v_mul_f32_e32 v4, v122, v4
	v_mul_f32_e32 v5, v123, v5
	v_lshlrev_b32_e32 v122, 16, v127
	v_and_b32_e32 v123, 0xffff0000, v127
	v_mul_f32_e32 v122, v124, v122
	v_mul_f32_e32 v123, v125, v123
	s_nop 0
	v_cvt_pk_bf16_f32 v4, v4, v5
	s_nop 0
	v_cvt_pk_bf16_f32 v5, v122, v123
	ds_read_b64 v[122:123], v2 offset:8480
	ds_write_b64 v2, v[4:5] offset:8448
	s_waitcnt lgkmcnt(1)
	v_lshlrev_b32_e32 v4, 16, v122
	v_and_b32_e32 v5, 0xffff0000, v122
	v_mul_f32_e32 v4, v118, v4
	v_mul_f32_e32 v5, v119, v5
	v_lshlrev_b32_e32 v118, 16, v123
	v_and_b32_e32 v119, 0xffff0000, v123
	v_mul_f32_e32 v118, v120, v118
	v_mul_f32_e32 v119, v121, v119
	s_nop 0
	v_cvt_pk_bf16_f32 v4, v4, v5
	s_nop 0
	v_cvt_pk_bf16_f32 v5, v118, v119
	ds_read_b64 v[118:119], v2 offset:16896
	ds_write_b64 v2, v[4:5] offset:8480
	s_waitcnt lgkmcnt(1)
	v_lshlrev_b32_e32 v4, 16, v118
	v_and_b32_e32 v5, 0xffff0000, v118
	v_mul_f32_e32 v4, v114, v4
	v_mul_f32_e32 v5, v115, v5
	v_lshlrev_b32_e32 v114, 16, v119
	v_and_b32_e32 v115, 0xffff0000, v119
	v_mul_f32_e32 v114, v116, v114
	v_mul_f32_e32 v115, v117, v115
	s_nop 0
	v_cvt_pk_bf16_f32 v4, v4, v5
	s_nop 0
	v_cvt_pk_bf16_f32 v5, v114, v115
	ds_read_b64 v[114:115], v2 offset:16928
	ds_write_b64 v2, v[4:5] offset:16896
	s_waitcnt lgkmcnt(1)
	v_lshlrev_b32_e32 v4, 16, v114
	v_and_b32_e32 v5, 0xffff0000, v114
	v_mul_f32_e32 v4, v110, v4
	v_mul_f32_e32 v5, v111, v5
	v_lshlrev_b32_e32 v110, 16, v115
	v_and_b32_e32 v111, 0xffff0000, v115
	v_mul_f32_e32 v110, v112, v110
	v_mul_f32_e32 v111, v113, v111
	s_nop 0
	v_cvt_pk_bf16_f32 v4, v4, v5
	s_nop 0
	v_cvt_pk_bf16_f32 v5, v110, v111
	ds_read_b64 v[110:111], v2 offset:25344
	ds_write_b64 v2, v[4:5] offset:16928
	s_waitcnt lgkmcnt(1)
	v_lshlrev_b32_e32 v4, 16, v110
	v_and_b32_e32 v5, 0xffff0000, v110
	v_mul_f32_e32 v4, v106, v4
	v_mul_f32_e32 v5, v107, v5
	v_lshlrev_b32_e32 v106, 16, v111
	v_and_b32_e32 v107, 0xffff0000, v111
	v_mul_f32_e32 v106, v108, v106
	v_mul_f32_e32 v107, v109, v107
	s_nop 0
	v_cvt_pk_bf16_f32 v4, v4, v5
	s_nop 0
	v_cvt_pk_bf16_f32 v5, v106, v107
	ds_read_b64 v[106:107], v2 offset:25376
	ds_write_b64 v2, v[4:5] offset:25344
	s_waitcnt lgkmcnt(1)
	v_lshlrev_b32_e32 v4, 16, v106
	v_and_b32_e32 v5, 0xffff0000, v106
	v_mul_f32_e32 v4, v102, v4
	v_mul_f32_e32 v5, v103, v5
	v_lshlrev_b32_e32 v102, 16, v107
	v_and_b32_e32 v103, 0xffff0000, v107
	v_mul_f32_e32 v102, v104, v102
	v_mul_f32_e32 v103, v105, v103
	s_nop 0
	v_cvt_pk_bf16_f32 v4, v4, v5
	s_nop 0
	v_cvt_pk_bf16_f32 v5, v102, v103
	ds_read_b64 v[102:103], v2 offset:256
	ds_write_b64 v2, v[4:5] offset:25376
	s_waitcnt lgkmcnt(1)
	v_lshlrev_b32_e32 v4, 16, v102
	v_and_b32_e32 v5, 0xffff0000, v102
	v_mul_f32_e32 v4, v98, v4
	v_mul_f32_e32 v5, v99, v5
	v_lshlrev_b32_e32 v98, 16, v103
	v_and_b32_e32 v99, 0xffff0000, v103
	v_mul_f32_e32 v98, v100, v98
	v_mul_f32_e32 v99, v101, v99
	s_nop 0
	v_cvt_pk_bf16_f32 v4, v4, v5
	s_nop 0
	v_cvt_pk_bf16_f32 v5, v98, v99
	ds_read_b64 v[98:99], v2 offset:288
	ds_write_b64 v2, v[4:5] offset:256
	s_waitcnt lgkmcnt(1)
	v_lshlrev_b32_e32 v4, 16, v98
	v_and_b32_e32 v5, 0xffff0000, v98
	v_mul_f32_e32 v4, v94, v4
	v_mul_f32_e32 v5, v95, v5
	v_lshlrev_b32_e32 v94, 16, v99
	v_and_b32_e32 v95, 0xffff0000, v99
	v_mul_f32_e32 v94, v96, v94
	v_mul_f32_e32 v95, v97, v95
	s_nop 0
	v_cvt_pk_bf16_f32 v4, v4, v5
	s_nop 0
	v_cvt_pk_bf16_f32 v5, v94, v95
	ds_read_b64 v[94:95], v2 offset:8704
	ds_write_b64 v2, v[4:5] offset:288
	s_waitcnt lgkmcnt(1)
	v_lshlrev_b32_e32 v4, 16, v94
	v_and_b32_e32 v5, 0xffff0000, v94
	v_mul_f32_e32 v4, v90, v4
	v_mul_f32_e32 v5, v91, v5
	v_lshlrev_b32_e32 v90, 16, v95
	v_and_b32_e32 v91, 0xffff0000, v95
	v_mul_f32_e32 v90, v92, v90
	v_mul_f32_e32 v91, v93, v91
	s_nop 0
	v_cvt_pk_bf16_f32 v4, v4, v5
	s_nop 0
	v_cvt_pk_bf16_f32 v5, v90, v91
	ds_read_b64 v[90:91], v2 offset:8736
	ds_write_b64 v2, v[4:5] offset:8704
	s_waitcnt lgkmcnt(1)
	v_lshlrev_b32_e32 v4, 16, v90
	v_and_b32_e32 v5, 0xffff0000, v90
	v_mul_f32_e32 v4, v86, v4
	v_mul_f32_e32 v5, v87, v5
	v_lshlrev_b32_e32 v86, 16, v91
	v_and_b32_e32 v87, 0xffff0000, v91
	v_mul_f32_e32 v86, v88, v86
	v_mul_f32_e32 v87, v89, v87
	s_nop 0
	v_cvt_pk_bf16_f32 v4, v4, v5
	s_nop 0
	v_cvt_pk_bf16_f32 v5, v86, v87
	ds_read_b64 v[86:87], v2 offset:17152
	ds_write_b64 v2, v[4:5] offset:8736
	s_waitcnt lgkmcnt(1)
	v_lshlrev_b32_e32 v4, 16, v86
	v_and_b32_e32 v5, 0xffff0000, v86
	v_mul_f32_e32 v4, v82, v4
	v_mul_f32_e32 v5, v83, v5
	v_lshlrev_b32_e32 v82, 16, v87
	v_and_b32_e32 v83, 0xffff0000, v87
	v_mul_f32_e32 v82, v84, v82
	v_mul_f32_e32 v83, v85, v83
	s_nop 0
	v_cvt_pk_bf16_f32 v4, v4, v5
	s_nop 0
	v_cvt_pk_bf16_f32 v5, v82, v83
	ds_read_b64 v[82:83], v2 offset:17184
	ds_write_b64 v2, v[4:5] offset:17152
	s_waitcnt lgkmcnt(1)
; __device__ __forceinline__ float bflo(unsigned v) { return __uint_as_float(v << 16); }
; __device__ __forceinline__ float bfhi(unsigned v) { return __uint_as_float(v & 0xffff0000u); }
; #define FOR_FRAG(ai, bj, m, n) _Pragma("unroll") for (int ai = 0; ai < 2; ++ai) _Pragma("unroll") for (int bj = 0; bj < 2; ++bj) \
;   _Pragma("unroll") for (int m = 0; m < 4; ++m) _Pragma("unroll") for (int n = 0; n < 2; ++n)
; __device__ __forceinline__ u32x2 pack4(float a, float b, float c, float d) { return u32x2{cvtpk(a, b), cvtpk(c, d)}; }
; __device__ __forceinline__ void phase4(const Params& p, char* shm) {
;     ...
;     FOR_FRAG(ai, bj, m, n) { u32x2* q = (u32x2*)(ctb + CT_OFF(ai, bj, m, n)); const u32x2 g = *q; const f32x4 v = acc[ai][bj][m][n];
;       *q = pack4(v[0] * bflo(g[0]), v[1] * bfhi(g[0]), v[2] * bflo(g[1]), v[3] * bfhi(g[1])); }
	v_lshlrev_b32_e32 v4, 16, v82
	v_and_b32_e32 v5, 0xffff0000, v82
	v_mul_f32_e32 v4, v78, v4
	v_mul_f32_e32 v5, v79, v5
	v_lshlrev_b32_e32 v78, 16, v83
	v_and_b32_e32 v79, 0xffff0000, v83
	v_mul_f32_e32 v78, v80, v78
	v_mul_f32_e32 v79, v81, v79
	s_nop 0
	v_cvt_pk_bf16_f32 v4, v4, v5
	s_nop 0
	v_cvt_pk_bf16_f32 v5, v78, v79
	ds_read_b64 v[78:79], v2 offset:25600
	ds_write_b64 v2, v[4:5] offset:17184
	s_waitcnt lgkmcnt(1)
	v_lshlrev_b32_e32 v4, 16, v78
	v_and_b32_e32 v5, 0xffff0000, v78
	v_mul_f32_e32 v4, v74, v4
	v_mul_f32_e32 v5, v75, v5
	v_lshlrev_b32_e32 v74, 16, v79
	v_and_b32_e32 v75, 0xffff0000, v79
	v_mul_f32_e32 v74, v76, v74
	v_mul_f32_e32 v75, v77, v75
	s_nop 0
	v_cvt_pk_bf16_f32 v4, v4, v5
	s_nop 0
	v_cvt_pk_bf16_f32 v5, v74, v75
	ds_read_b64 v[74:75], v2 offset:25632
	ds_write_b64 v2, v[4:5] offset:25600
	s_waitcnt lgkmcnt(1)
	v_lshlrev_b32_e32 v4, 16, v74
	v_and_b32_e32 v5, 0xffff0000, v74
	v_mul_f32_e32 v4, v70, v4
	v_mul_f32_e32 v5, v71, v5
	v_lshlrev_b32_e32 v70, 16, v75
	v_and_b32_e32 v71, 0xffff0000, v75
	v_mul_f32_e32 v70, v72, v70
	v_mul_f32_e32 v71, v73, v71
	v_add_u32_e32 v72, 0x10800, v2
	s_nop 0
	v_cvt_pk_bf16_f32 v4, v4, v5
	s_nop 0
	v_cvt_pk_bf16_f32 v5, v70, v71
	ds_read_b64 v[70:71], v72
	ds_write_b64 v2, v[4:5] offset:25632
	s_waitcnt lgkmcnt(1)
	v_lshlrev_b32_e32 v4, 16, v70
	v_and_b32_e32 v5, 0xffff0000, v70
	v_mul_f32_e32 v4, v66, v4
	v_mul_f32_e32 v5, v67, v5
	v_lshlrev_b32_e32 v66, 16, v71
	v_and_b32_e32 v67, 0xffff0000, v71
	v_mul_f32_e32 v66, v68, v66
	v_mul_f32_e32 v67, v69, v67
	v_add_u32_e32 v68, 0x10820, v2
	s_nop 0
	v_cvt_pk_bf16_f32 v4, v4, v5
	s_nop 0
	v_cvt_pk_bf16_f32 v5, v66, v67
	ds_read_b64 v[66:67], v68
	ds_write_b64 v72, v[4:5]
	s_waitcnt lgkmcnt(1)
	v_lshlrev_b32_e32 v4, 16, v66
	v_and_b32_e32 v5, 0xffff0000, v66
	v_mul_f32_e32 v4, v62, v4
	v_mul_f32_e32 v5, v63, v5
	v_lshlrev_b32_e32 v62, 16, v67
	v_and_b32_e32 v63, 0xffff0000, v67
	v_mul_f32_e32 v62, v64, v62
	v_mul_f32_e32 v63, v65, v63
	v_add_u32_e32 v64, 0x12900, v2
	s_nop 0
	v_cvt_pk_bf16_f32 v4, v4, v5
	s_nop 0
	v_cvt_pk_bf16_f32 v5, v62, v63
	ds_read_b64 v[62:63], v64
	ds_write_b64 v68, v[4:5]
	s_waitcnt lgkmcnt(1)
	v_lshlrev_b32_e32 v4, 16, v62
	v_and_b32_e32 v5, 0xffff0000, v62
	v_mul_f32_e32 v4, v58, v4
	v_mul_f32_e32 v5, v59, v5
	v_lshlrev_b32_e32 v58, 16, v63
	v_and_b32_e32 v59, 0xffff0000, v63
	v_mul_f32_e32 v58, v60, v58
	v_mul_f32_e32 v59, v61, v59
	v_add_u32_e32 v60, 0x12920, v2
	s_nop 0
	v_cvt_pk_bf16_f32 v4, v4, v5
	s_nop 0
	v_cvt_pk_bf16_f32 v5, v58, v59
	ds_read_b64 v[58:59], v60
	ds_write_b64 v64, v[4:5]
	s_waitcnt lgkmcnt(1)
	v_lshlrev_b32_e32 v4, 16, v58
	v_and_b32_e32 v5, 0xffff0000, v58
	v_mul_f32_e32 v4, v54, v4
	v_mul_f32_e32 v5, v55, v5
	v_lshlrev_b32_e32 v54, 16, v59
	v_and_b32_e32 v55, 0xffff0000, v59
	v_mul_f32_e32 v54, v56, v54
	v_mul_f32_e32 v55, v57, v55
	v_add_u32_e32 v56, 0x14a00, v2
	s_nop 0
	v_cvt_pk_bf16_f32 v4, v4, v5
	s_nop 0
	v_cvt_pk_bf16_f32 v5, v54, v55
	ds_read_b64 v[54:55], v56
	ds_write_b64 v60, v[4:5]
	s_waitcnt lgkmcnt(1)
	v_lshlrev_b32_e32 v4, 16, v54
	v_and_b32_e32 v5, 0xffff0000, v54
	v_mul_f32_e32 v4, v50, v4
	v_mul_f32_e32 v5, v51, v5
	v_lshlrev_b32_e32 v50, 16, v55
	v_and_b32_e32 v51, 0xffff0000, v55
	v_mul_f32_e32 v50, v52, v50
	v_mul_f32_e32 v51, v53, v51
	v_add_u32_e32 v52, 0x14a20, v2
	s_nop 0
	v_cvt_pk_bf16_f32 v4, v4, v5
	s_nop 0
	v_cvt_pk_bf16_f32 v5, v50, v51
	ds_read_b64 v[50:51], v52
	ds_write_b64 v56, v[4:5]
	s_waitcnt lgkmcnt(1)
	v_lshlrev_b32_e32 v4, 16, v50
	v_and_b32_e32 v5, 0xffff0000, v50
	v_mul_f32_e32 v4, v46, v4
	v_mul_f32_e32 v5, v47, v5
	v_lshlrev_b32_e32 v46, 16, v51
	v_and_b32_e32 v47, 0xffff0000, v51
	v_mul_f32_e32 v46, v48, v46
	v_mul_f32_e32 v47, v49, v47
	v_add_u32_e32 v48, 0x16b00, v2
	s_nop 0
	v_cvt_pk_bf16_f32 v4, v4, v5
	s_nop 0
	v_cvt_pk_bf16_f32 v5, v46, v47
	ds_read_b64 v[46:47], v48
	ds_write_b64 v52, v[4:5]
	s_waitcnt lgkmcnt(1)
	v_lshlrev_b32_e32 v4, 16, v46
	v_and_b32_e32 v5, 0xffff0000, v46
	v_mul_f32_e32 v4, v42, v4
	v_mul_f32_e32 v5, v43, v5
	v_lshlrev_b32_e32 v42, 16, v47
	v_and_b32_e32 v43, 0xffff0000, v47
	v_mul_f32_e32 v42, v44, v42
	v_mul_f32_e32 v43, v45, v43
	v_add_u32_e32 v44, 0x16b20, v2
	s_nop 0
	v_cvt_pk_bf16_f32 v4, v4, v5
	s_nop 0
	v_cvt_pk_bf16_f32 v5, v42, v43
	ds_read_b64 v[42:43], v44
	ds_write_b64 v48, v[4:5]
	s_waitcnt lgkmcnt(1)
; __device__ __forceinline__ float bflo(unsigned v) { return __uint_as_float(v << 16); }
; __device__ __forceinline__ float bfhi(unsigned v) { return __uint_as_float(v & 0xffff0000u); }
; __device__ __forceinline__ int opq(int x) { asm volatile("" : "+v"(x)); return x; }
; #define FOR_FRAG(ai, bj, m, n) _Pragma("unroll") for (int ai = 0; ai < 2; ++ai) _Pragma("unroll") for (int bj = 0; bj < 2; ++bj) \
;   _Pragma("unroll") for (int m = 0; m < 4; ++m) _Pragma("unroll") for (int n = 0; n < 2; ++n)
; __device__ __forceinline__ u32x2 pack4(float a, float b, float c, float d) { return u32x2{cvtpk(a, b), cvtpk(c, d)}; }
; __device__ __forceinline__ void ct_store(const char* shm, u16* __restrict__ dst, const int ldd, const int cl2, const int lcol0) {
;     ...
;   for (int id = opq((int)threadIdx.x); id < n; id += NTHR) {
;     const int row = id >> cl2, c = id & ((1 << cl2) - 1);
;     const u32x4 v = *reinterpret_cast<const u32x4*>(shm + (row * CT_LD + lcol0 + c * 8) * 2);
;     *reinterpret_cast<u32x4*>(dst + (size_t)row * ldd + c * 8) = v;
; __device__ __forceinline__ void phase4(const Params& p, char* shm) {
;     ...
;     FOR_FRAG(ai, bj, m, n) { u32x2* q = (u32x2*)(ctb + CT_OFF(ai, bj, m, n)); const u32x2 g = *q; const f32x4 v = acc[ai][bj][m][n];
;       *q = pack4(v[0] * bflo(g[0]), v[1] * bfhi(g[0]), v[2] * bflo(g[1]), v[3] * bfhi(g[1])); }
;     __syncthreads();
;     ct_store(shm, Mg + brow * DM + bcol, DM, 5, 0);
	v_lshlrev_b32_e32 v4, 16, v42
	v_and_b32_e32 v5, 0xffff0000, v42
	v_mul_f32_e32 v4, v38, v4
	v_mul_f32_e32 v5, v39, v5
	v_lshlrev_b32_e32 v38, 16, v43
	v_and_b32_e32 v39, 0xffff0000, v43
	v_mul_f32_e32 v38, v40, v38
	v_mul_f32_e32 v39, v41, v39
	v_add_u32_e32 v40, 0x10900, v2
	s_nop 0
	v_cvt_pk_bf16_f32 v4, v4, v5
	s_nop 0
	v_cvt_pk_bf16_f32 v5, v38, v39
	ds_read_b64 v[38:39], v40
	ds_write_b64 v44, v[4:5]
	s_waitcnt lgkmcnt(1)
	v_lshlrev_b32_e32 v4, 16, v38
	v_and_b32_e32 v5, 0xffff0000, v38
	v_mul_f32_e32 v4, v34, v4
	v_mul_f32_e32 v5, v35, v5
	v_lshlrev_b32_e32 v34, 16, v39
	v_and_b32_e32 v35, 0xffff0000, v39
	v_mul_f32_e32 v34, v36, v34
	v_mul_f32_e32 v35, v37, v35
	v_add_u32_e32 v36, 0x10920, v2
	s_nop 0
	v_cvt_pk_bf16_f32 v4, v4, v5
	s_nop 0
	v_cvt_pk_bf16_f32 v5, v34, v35
	ds_read_b64 v[34:35], v36
	ds_write_b64 v40, v[4:5]
	s_waitcnt lgkmcnt(1)
	v_lshlrev_b32_e32 v4, 16, v34
	v_and_b32_e32 v5, 0xffff0000, v34
	v_mul_f32_e32 v4, v30, v4
	v_mul_f32_e32 v5, v31, v5
	v_lshlrev_b32_e32 v30, 16, v35
	v_and_b32_e32 v31, 0xffff0000, v35
	v_mul_f32_e32 v30, v32, v30
	v_mul_f32_e32 v31, v33, v31
	v_add_u32_e32 v32, 0x12a00, v2
	s_nop 0
	v_cvt_pk_bf16_f32 v4, v4, v5
	s_nop 0
	v_cvt_pk_bf16_f32 v5, v30, v31
	ds_read_b64 v[30:31], v32
	ds_write_b64 v36, v[4:5]
	s_waitcnt lgkmcnt(1)
	v_lshlrev_b32_e32 v4, 16, v30
	v_and_b32_e32 v5, 0xffff0000, v30
	v_mul_f32_e32 v4, v26, v4
	v_mul_f32_e32 v5, v27, v5
	v_lshlrev_b32_e32 v26, 16, v31
	v_and_b32_e32 v27, 0xffff0000, v31
	v_mul_f32_e32 v26, v28, v26
	v_mul_f32_e32 v27, v29, v27
	v_add_u32_e32 v28, 0x12a20, v2
	s_nop 0
	v_cvt_pk_bf16_f32 v4, v4, v5
	s_nop 0
	v_cvt_pk_bf16_f32 v5, v26, v27
	ds_read_b64 v[26:27], v28
	ds_write_b64 v32, v[4:5]
	s_waitcnt lgkmcnt(1)
	v_lshlrev_b32_e32 v4, 16, v26
	v_and_b32_e32 v5, 0xffff0000, v26
	v_mul_f32_e32 v4, v22, v4
	v_mul_f32_e32 v5, v23, v5
	v_lshlrev_b32_e32 v22, 16, v27
	v_and_b32_e32 v23, 0xffff0000, v27
	v_mul_f32_e32 v22, v24, v22
	v_mul_f32_e32 v23, v25, v23
	v_add_u32_e32 v24, 0x14b00, v2
	s_nop 0
	v_cvt_pk_bf16_f32 v4, v4, v5
	s_nop 0
	v_cvt_pk_bf16_f32 v5, v22, v23
	ds_read_b64 v[22:23], v24
	ds_write_b64 v28, v[4:5]
	s_waitcnt lgkmcnt(1)
	v_lshlrev_b32_e32 v4, 16, v22
	v_and_b32_e32 v5, 0xffff0000, v22
	v_mul_f32_e32 v4, v18, v4
	v_mul_f32_e32 v5, v19, v5
	v_lshlrev_b32_e32 v18, 16, v23
	v_and_b32_e32 v19, 0xffff0000, v23
	v_mul_f32_e32 v18, v20, v18
	v_mul_f32_e32 v19, v21, v19
	v_add_u32_e32 v20, 0x14b20, v2
	s_nop 0
	v_cvt_pk_bf16_f32 v4, v4, v5
	s_nop 0
	v_cvt_pk_bf16_f32 v5, v18, v19
	ds_read_b64 v[18:19], v20
	ds_write_b64 v24, v[4:5]
	s_waitcnt lgkmcnt(1)
	v_lshlrev_b32_e32 v4, 16, v18
	v_and_b32_e32 v5, 0xffff0000, v18
	v_mul_f32_e32 v4, v14, v4
	v_mul_f32_e32 v5, v15, v5
	v_lshlrev_b32_e32 v14, 16, v19
	v_and_b32_e32 v15, 0xffff0000, v19
	v_mul_f32_e32 v14, v16, v14
	v_mul_f32_e32 v15, v17, v15
	v_add_u32_e32 v16, 0x16c00, v2
	s_nop 0
	v_cvt_pk_bf16_f32 v4, v4, v5
	s_nop 0
	v_cvt_pk_bf16_f32 v5, v14, v15
	ds_read_b64 v[14:15], v16
	ds_write_b64 v20, v[4:5]
	v_add_u32_e32 v2, 0x16c20, v2
	s_waitcnt lgkmcnt(1)
	v_lshlrev_b32_e32 v4, 16, v14
	v_and_b32_e32 v5, 0xffff0000, v14
	v_mul_f32_e32 v4, v10, v4
	v_mul_f32_e32 v5, v11, v5
	v_lshlrev_b32_e32 v10, 16, v15
	v_and_b32_e32 v11, 0xffff0000, v15
	v_mul_f32_e32 v10, v12, v10
	v_mul_f32_e32 v11, v13, v11
	s_nop 0
	v_cvt_pk_bf16_f32 v4, v4, v5
	s_nop 0
	v_cvt_pk_bf16_f32 v5, v10, v11
	ds_read_b64 v[10:11], v2
	ds_write_b64 v16, v[4:5]
	s_waitcnt lgkmcnt(1)
	v_lshlrev_b32_e32 v4, 16, v10
	v_mul_f32_e32 v4, v6, v4
	v_and_b32_e32 v5, 0xffff0000, v10
	v_mul_f32_e32 v5, v7, v5
	v_lshlrev_b32_e32 v6, 16, v11
	v_and_b32_e32 v7, 0xffff0000, v11
	s_nop 0
	v_cvt_pk_bf16_f32 v4, v4, v5
	v_mul_f32_e32 v6, v8, v6
	v_mul_f32_e32 v7, v9, v7
	s_nop 0
	v_cvt_pk_bf16_f32 v5, v6, v7
	ds_write_b64 v2, v[4:5]
	v_mov_b32_e32 v4, v1
	s_waitcnt lgkmcnt(0)
	s_barrier
	s_nop 0
	v_cmp_gt_i32_e32 vcc, s45, v4
	s_and_saveexec_b64 s[8:9], vcc
	s_cbranch_execz .LBB0_448
	s_lshl_b64 s[6:7], s[6:7], 20
	v_max_i32_e32 v2, 0x1e00, v4
	s_add_u32 s6, s3, s6
	v_sub_u32_e32 v2, v2, v4
	s_addc_u32 s7, s38, s7
	v_add_u32_e32 v5, 0x1ff, v2
	s_add_u32 s6, s6, s12
	v_and_b32_e32 v2, 0x600, v5
	s_addc_u32 s7, s7, 0
	v_cmp_ne_u32_e32 vcc, s53, v2
	s_and_saveexec_b64 s[12:13], vcc
	s_cbranch_execz .LBB0_464
	v_lshrrev_b32_e32 v2, 9, v5
	v_add_u32_e32 v2, 1, v2
	v_and_b32_e32 v2, 3, v2
	v_lshlrev_b32_e32 v6, 3, v4
	v_sub_u32_e32 v7, 0, v2
	s_mov_b64 s[14:15], 0
